# o5 + removed mid-burst s_setprio 0/1 flip pairs in all GEMM K-loops (28 sites)
# speedup vs baseline: 1.0079x; 1.0079x over previous
.LBB0_203:
	ds_read_b128 v[152:155], v148
	ds_read_b128 v[156:159], v148 offset:1024
	ds_read_b128 v[160:163], v148 offset:2048
	ds_read_b128 v[164:167], v148 offset:3072
	ds_read_b128 v[168:171], v149
	ds_read_b128 v[172:175], v149 offset:1024
	ds_read_b128 v[176:179], v149 offset:2048
	ds_read_b128 v[180:183], v149 offset:3072
	s_add_u32 s26, s24, 0xfff80080
	s_addc_u32 s27, s25, -1
	s_cmp_eq_u32 s50, 28
	s_cselect_b32 s29, s11, s27
	s_cselect_b32 s28, s46, s26
	s_cselect_b32 s27, s9, s49
	s_cselect_b32 s26, s47, s48
	v_lshl_add_u64 v[200:201], s[24:25], 0, v[138:139]
	s_add_i32 m0, s17, 0xc000
	ds_read_b128 v[184:187], v150
	ds_read_b128 v[188:191], v150 offset:1024
	ds_read_b128 v[192:195], v150 offset:2048
	ds_read_b128 v[196:199], v150 offset:3072
	ds_read_b128 v[204:207], v150 offset:4096
	ds_read_b128 v[208:211], v150 offset:5120
	ds_read_b128 v[212:215], v150 offset:6144
	ds_read_b128 v[216:219], v150 offset:7168
	global_load_lds_dwordx4 v[200:201], off
	v_lshl_add_u64 v[200:201], s[24:25], 0, v[140:141]
	s_add_i32 m0, s17, 0xe000
	s_nop 0
	global_load_lds_dwordx4 v[200:201], off
	s_waitcnt vmcnt(8)
	s_waitcnt lgkmcnt(0)
	s_barrier
	s_setprio 1
	s_waitcnt lgkmcnt(0)
	v_mfma_f32_16x16x32_bf16 v[126:129], v[152:155], v[184:187], v[126:129]
	v_mfma_f32_16x16x32_bf16 v[122:125], v[160:163], v[184:187], v[122:125]
	v_mfma_f32_16x16x32_bf16 v[110:113], v[152:155], v[192:195], v[110:113]
	v_mfma_f32_16x16x32_bf16 v[106:109], v[160:163], v[192:195], v[106:109]
	v_mfma_f32_16x16x32_bf16 v[94:97], v[152:155], v[204:207], v[94:97]
	v_mfma_f32_16x16x32_bf16 v[90:93], v[160:163], v[204:207], v[90:93]
	v_mfma_f32_16x16x32_bf16 v[78:81], v[152:155], v[212:215], v[78:81]
	v_mfma_f32_16x16x32_bf16 v[74:77], v[160:163], v[212:215], v[74:77]
	v_mfma_f32_16x16x32_bf16 v[126:129], v[156:159], v[188:191], v[126:129]
	v_mfma_f32_16x16x32_bf16 v[122:125], v[164:167], v[188:191], v[122:125]
	v_mfma_f32_16x16x32_bf16 v[110:113], v[156:159], v[196:199], v[110:113]
	v_mfma_f32_16x16x32_bf16 v[106:109], v[164:167], v[196:199], v[106:109]
	v_mfma_f32_16x16x32_bf16 v[94:97], v[156:159], v[208:211], v[94:97]
	v_mfma_f32_16x16x32_bf16 v[90:93], v[164:167], v[208:211], v[90:93]
	v_mfma_f32_16x16x32_bf16 v[78:81], v[156:159], v[216:219], v[78:81]
	v_mfma_f32_16x16x32_bf16 v[74:77], v[164:167], v[216:219], v[74:77]
	v_mfma_f32_16x16x32_bf16 v[118:121], v[168:171], v[184:187], v[118:121]
	v_mfma_f32_16x16x32_bf16 v[114:117], v[176:179], v[184:187], v[114:117]
	v_mfma_f32_16x16x32_bf16 v[102:105], v[168:171], v[192:195], v[102:105]
	v_mfma_f32_16x16x32_bf16 v[98:101], v[176:179], v[192:195], v[98:101]
	v_mfma_f32_16x16x32_bf16 v[86:89], v[168:171], v[204:207], v[86:89]
	v_mfma_f32_16x16x32_bf16 v[82:85], v[176:179], v[204:207], v[82:85]
	v_mfma_f32_16x16x32_bf16 v[70:73], v[168:171], v[212:215], v[70:73]
	v_mfma_f32_16x16x32_bf16 v[66:69], v[176:179], v[212:215], v[66:69]
	v_mfma_f32_16x16x32_bf16 v[118:121], v[172:175], v[188:191], v[118:121]
	v_mfma_f32_16x16x32_bf16 v[114:117], v[180:183], v[188:191], v[114:117]
	v_mfma_f32_16x16x32_bf16 v[102:105], v[172:175], v[196:199], v[102:105]
	v_mfma_f32_16x16x32_bf16 v[98:101], v[180:183], v[196:199], v[98:101]
	v_mfma_f32_16x16x32_bf16 v[86:89], v[172:175], v[208:211], v[86:89]
	v_mfma_f32_16x16x32_bf16 v[82:85], v[180:183], v[208:211], v[82:85]
	v_mfma_f32_16x16x32_bf16 v[70:73], v[172:175], v[216:219], v[70:73]
	v_mfma_f32_16x16x32_bf16 v[66:69], v[180:183], v[216:219], v[66:69]
	s_setprio 0
	s_barrier
	s_add_i32 s51, s42, s34
	v_lshl_add_u64 v[200:201], s[26:27], 0, v[132:133]
	s_mov_b32 m0, s51
	ds_read_b128 v[184:187], v150 offset:16384
	ds_read_b128 v[188:191], v150 offset:17408
	ds_read_b128 v[192:195], v150 offset:18432
	ds_read_b128 v[196:199], v150 offset:19456
	ds_read_b128 v[204:207], v150 offset:20480
	ds_read_b128 v[208:211], v150 offset:21504
	ds_read_b128 v[212:215], v150 offset:22528
	ds_read_b128 v[216:219], v150 offset:23552
	global_load_lds_dwordx4 v[200:201], off
	s_add_i32 m0, s51, 0x2000
	s_add_u32 s52, s26, 0x80000
	v_lshl_add_u64 v[220:221], s[26:27], 0, v[136:137]
	s_addc_u32 s53, s27, 0
	s_add_i32 s51, s43, s34
	global_load_lds_dwordx4 v[220:221], off
	v_lshl_add_u64 v[222:223], s[52:53], 0, v[132:133]
	s_mov_b32 m0, s51
	v_lshl_add_u64 v[224:225], s[28:29], 0, v[134:135]
	global_load_lds_dwordx4 v[222:223], off
	v_lshl_add_u64 v[222:223], s[52:53], 0, v[136:137]
	s_add_i32 m0, s51, 0x2000
	s_nop 0
	global_load_lds_dwordx4 v[222:223], off
	v_lshl_add_u64 v[222:223], s[28:29], 0, v[130:131]
	s_mov_b32 m0, s17
	s_nop 0
	global_load_lds_dwordx4 v[222:223], off
	s_mov_b32 m0, s35
	s_nop 0
	global_load_lds_dwordx4 v[224:225], off
	s_waitcnt vmcnt(8)
	s_waitcnt lgkmcnt(0)
	s_barrier
	s_setprio 1
	s_waitcnt lgkmcnt(0)
	v_mfma_f32_16x16x32_bf16 v[62:65], v[152:155], v[184:187], v[62:65]
	v_mfma_f32_16x16x32_bf16 v[58:61], v[160:163], v[184:187], v[58:61]
	v_mfma_f32_16x16x32_bf16 v[46:49], v[152:155], v[192:195], v[46:49]
	v_mfma_f32_16x16x32_bf16 v[42:45], v[160:163], v[192:195], v[42:45]
	v_mfma_f32_16x16x32_bf16 v[30:33], v[152:155], v[204:207], v[30:33]
	v_mfma_f32_16x16x32_bf16 v[26:29], v[160:163], v[204:207], v[26:29]
	v_mfma_f32_16x16x32_bf16 v[14:17], v[152:155], v[212:215], v[14:17]
	v_mfma_f32_16x16x32_bf16 v[10:13], v[160:163], v[212:215], v[10:13]
	v_mfma_f32_16x16x32_bf16 v[62:65], v[156:159], v[188:191], v[62:65]
	v_mfma_f32_16x16x32_bf16 v[58:61], v[164:167], v[188:191], v[58:61]
	v_mfma_f32_16x16x32_bf16 v[46:49], v[156:159], v[196:199], v[46:49]
	v_mfma_f32_16x16x32_bf16 v[42:45], v[164:167], v[196:199], v[42:45]
	v_mfma_f32_16x16x32_bf16 v[30:33], v[156:159], v[208:211], v[30:33]
	v_mfma_f32_16x16x32_bf16 v[26:29], v[164:167], v[208:211], v[26:29]
	v_mfma_f32_16x16x32_bf16 v[14:17], v[156:159], v[216:219], v[14:17]
	v_mfma_f32_16x16x32_bf16 v[10:13], v[164:167], v[216:219], v[10:13]
	v_mfma_f32_16x16x32_bf16 v[54:57], v[168:171], v[184:187], v[54:57]
	v_mfma_f32_16x16x32_bf16 v[50:53], v[176:179], v[184:187], v[50:53]
	v_mfma_f32_16x16x32_bf16 v[38:41], v[168:171], v[192:195], v[38:41]
	v_mfma_f32_16x16x32_bf16 v[34:37], v[176:179], v[192:195], v[34:37]
	v_mfma_f32_16x16x32_bf16 v[22:25], v[168:171], v[204:207], v[22:25]
	v_mfma_f32_16x16x32_bf16 v[18:21], v[176:179], v[204:207], v[18:21]
	v_mfma_f32_16x16x32_bf16 v[6:9], v[168:171], v[212:215], v[6:9]
	v_mfma_f32_16x16x32_bf16 v[2:5], v[176:179], v[212:215], v[2:5]
	v_mfma_f32_16x16x32_bf16 v[54:57], v[172:175], v[188:191], v[54:57]
	v_mfma_f32_16x16x32_bf16 v[50:53], v[180:183], v[188:191], v[50:53]
	v_mfma_f32_16x16x32_bf16 v[38:41], v[172:175], v[196:199], v[38:41]
	v_mfma_f32_16x16x32_bf16 v[34:37], v[180:183], v[196:199], v[34:37]
	v_mfma_f32_16x16x32_bf16 v[22:25], v[172:175], v[208:211], v[22:25]
	v_mfma_f32_16x16x32_bf16 v[18:21], v[180:183], v[208:211], v[18:21]
	v_mfma_f32_16x16x32_bf16 v[6:9], v[172:175], v[216:219], v[6:9]
	v_mfma_f32_16x16x32_bf16 v[2:5], v[180:183], v[216:219], v[2:5]
	s_setprio 0
	s_barrier
	s_add_i32 s51, 0, 0x18000
	v_add_u32_e32 v151, s51, v146
	s_add_i32 s52, 0, 0x1c000
	ds_read_b128 v[152:155], v151
	ds_read_b128 v[156:159], v151 offset:1024
	ds_read_b128 v[160:163], v151 offset:2048
	ds_read_b128 v[164:167], v151 offset:3072
	v_add_u32_e32 v151, s52, v146
	ds_read_b128 v[168:171], v151
	ds_read_b128 v[172:175], v151 offset:1024
	ds_read_b128 v[176:179], v151 offset:2048
	ds_read_b128 v[180:183], v151 offset:3072
	s_add_u32 s28, s28, 0x80000
	s_addc_u32 s29, s29, 0
	s_mov_b32 m0, s36
	v_lshl_add_u64 v[226:227], s[28:29], 0, v[130:131]
	ds_read_b128 v[184:187], v150 offset:32768
	ds_read_b128 v[188:191], v150 offset:33792
	ds_read_b128 v[192:195], v150 offset:34816
	ds_read_b128 v[196:199], v150 offset:35840
	ds_read_b128 v[204:207], v150 offset:36864
	ds_read_b128 v[208:211], v150 offset:37888
	ds_read_b128 v[212:215], v150 offset:38912
	ds_read_b128 v[216:219], v150 offset:39936
	global_load_lds_dwordx4 v[226:227], off
	v_lshl_add_u64 v[226:227], s[28:29], 0, v[134:135]
	s_mov_b32 m0, s37
	s_nop 0
	global_load_lds_dwordx4 v[226:227], off
	s_waitcnt vmcnt(8)
	s_waitcnt lgkmcnt(0)
	s_barrier
	s_setprio 1
	s_waitcnt lgkmcnt(0)
	v_mfma_f32_16x16x32_bf16 v[126:129], v[152:155], v[184:187], v[126:129]
	v_mfma_f32_16x16x32_bf16 v[122:125], v[160:163], v[184:187], v[122:125]
	v_mfma_f32_16x16x32_bf16 v[110:113], v[152:155], v[192:195], v[110:113]
	v_mfma_f32_16x16x32_bf16 v[106:109], v[160:163], v[192:195], v[106:109]
	v_mfma_f32_16x16x32_bf16 v[94:97], v[152:155], v[204:207], v[94:97]
	v_mfma_f32_16x16x32_bf16 v[90:93], v[160:163], v[204:207], v[90:93]
	v_mfma_f32_16x16x32_bf16 v[78:81], v[152:155], v[212:215], v[78:81]
	v_mfma_f32_16x16x32_bf16 v[74:77], v[160:163], v[212:215], v[74:77]
	v_mfma_f32_16x16x32_bf16 v[126:129], v[156:159], v[188:191], v[126:129]
	v_mfma_f32_16x16x32_bf16 v[122:125], v[164:167], v[188:191], v[122:125]
	v_mfma_f32_16x16x32_bf16 v[110:113], v[156:159], v[196:199], v[110:113]
	v_mfma_f32_16x16x32_bf16 v[106:109], v[164:167], v[196:199], v[106:109]
	v_mfma_f32_16x16x32_bf16 v[94:97], v[156:159], v[208:211], v[94:97]
	v_mfma_f32_16x16x32_bf16 v[90:93], v[164:167], v[208:211], v[90:93]
	v_mfma_f32_16x16x32_bf16 v[78:81], v[156:159], v[216:219], v[78:81]
	v_mfma_f32_16x16x32_bf16 v[74:77], v[164:167], v[216:219], v[74:77]
	v_mfma_f32_16x16x32_bf16 v[118:121], v[168:171], v[184:187], v[118:121]
	v_mfma_f32_16x16x32_bf16 v[114:117], v[176:179], v[184:187], v[114:117]
	v_mfma_f32_16x16x32_bf16 v[102:105], v[168:171], v[192:195], v[102:105]
	v_mfma_f32_16x16x32_bf16 v[98:101], v[176:179], v[192:195], v[98:101]
	v_mfma_f32_16x16x32_bf16 v[86:89], v[168:171], v[204:207], v[86:89]
	v_mfma_f32_16x16x32_bf16 v[82:85], v[176:179], v[204:207], v[82:85]
	v_mfma_f32_16x16x32_bf16 v[70:73], v[168:171], v[212:215], v[70:73]
	v_mfma_f32_16x16x32_bf16 v[66:69], v[176:179], v[212:215], v[66:69]
	v_mfma_f32_16x16x32_bf16 v[118:121], v[172:175], v[188:191], v[118:121]
	v_mfma_f32_16x16x32_bf16 v[114:117], v[180:183], v[188:191], v[114:117]
	v_mfma_f32_16x16x32_bf16 v[102:105], v[172:175], v[196:199], v[102:105]
	v_mfma_f32_16x16x32_bf16 v[98:101], v[180:183], v[196:199], v[98:101]
	v_mfma_f32_16x16x32_bf16 v[86:89], v[172:175], v[208:211], v[86:89]
	v_mfma_f32_16x16x32_bf16 v[82:85], v[180:183], v[208:211], v[82:85]
	v_mfma_f32_16x16x32_bf16 v[70:73], v[172:175], v[216:219], v[70:73]
	v_mfma_f32_16x16x32_bf16 v[66:69], v[180:183], v[216:219], v[66:69]
	s_setprio 0
	s_barrier
	s_add_i32 s28, s51, s34
	v_lshl_add_u64 v[200:201], v[200:201], 0, s[4:5]
	s_mov_b32 m0, s28
	ds_read_b128 v[184:187], v150 offset:49152
	ds_read_b128 v[188:191], v150 offset:50176
	ds_read_b128 v[192:195], v150 offset:51200
	ds_read_b128 v[196:199], v150 offset:52224
	ds_read_b128 v[204:207], v150 offset:53248
	ds_read_b128 v[208:211], v150 offset:54272
	ds_read_b128 v[212:215], v150 offset:55296
	ds_read_b128 v[216:219], v150 offset:56320
	global_load_lds_dwordx4 v[200:201], off
	s_add_i32 m0, s28, 0x2000
	s_add_u32 s26, s26, 0x80080
	v_lshl_add_u64 v[200:201], v[220:221], 0, s[4:5]
	s_addc_u32 s27, s27, 0
	s_add_i32 s28, s52, s34
	global_load_lds_dwordx4 v[200:201], off
	v_lshl_add_u64 v[200:201], s[26:27], 0, v[132:133]
	s_mov_b32 m0, s28
	s_nop 0
	global_load_lds_dwordx4 v[200:201], off
	v_lshl_add_u64 v[200:201], s[26:27], 0, v[136:137]
	s_add_i32 m0, s28, 0x2000
	s_nop 0
	global_load_lds_dwordx4 v[200:201], off
	v_lshl_add_u64 v[200:201], v[222:223], 0, s[4:5]
	s_mov_b32 m0, s39
	s_nop 0
	global_load_lds_dwordx4 v[200:201], off
	v_lshl_add_u64 v[200:201], v[224:225], 0, s[4:5]
	s_mov_b32 m0, s40
	s_nop 0
	global_load_lds_dwordx4 v[200:201], off
	s_waitcnt vmcnt(8)
	s_waitcnt lgkmcnt(0)
	s_barrier
	s_setprio 1
	s_waitcnt lgkmcnt(0)
	v_mfma_f32_16x16x32_bf16 v[62:65], v[152:155], v[184:187], v[62:65]
	v_mfma_f32_16x16x32_bf16 v[58:61], v[160:163], v[184:187], v[58:61]
	v_mfma_f32_16x16x32_bf16 v[46:49], v[152:155], v[192:195], v[46:49]
	v_mfma_f32_16x16x32_bf16 v[42:45], v[160:163], v[192:195], v[42:45]
	v_mfma_f32_16x16x32_bf16 v[30:33], v[152:155], v[204:207], v[30:33]
	v_mfma_f32_16x16x32_bf16 v[26:29], v[160:163], v[204:207], v[26:29]
	v_mfma_f32_16x16x32_bf16 v[14:17], v[152:155], v[212:215], v[14:17]
	v_mfma_f32_16x16x32_bf16 v[10:13], v[160:163], v[212:215], v[10:13]
	v_mfma_f32_16x16x32_bf16 v[62:65], v[156:159], v[188:191], v[62:65]
	v_mfma_f32_16x16x32_bf16 v[58:61], v[164:167], v[188:191], v[58:61]
	v_mfma_f32_16x16x32_bf16 v[46:49], v[156:159], v[196:199], v[46:49]
	v_mfma_f32_16x16x32_bf16 v[42:45], v[164:167], v[196:199], v[42:45]
	v_mfma_f32_16x16x32_bf16 v[30:33], v[156:159], v[208:211], v[30:33]
	v_mfma_f32_16x16x32_bf16 v[26:29], v[164:167], v[208:211], v[26:29]
	v_mfma_f32_16x16x32_bf16 v[14:17], v[156:159], v[216:219], v[14:17]
	v_mfma_f32_16x16x32_bf16 v[10:13], v[164:167], v[216:219], v[10:13]
	v_mfma_f32_16x16x32_bf16 v[54:57], v[168:171], v[184:187], v[54:57]
	v_mfma_f32_16x16x32_bf16 v[50:53], v[176:179], v[184:187], v[50:53]
	v_mfma_f32_16x16x32_bf16 v[38:41], v[168:171], v[192:195], v[38:41]
	v_mfma_f32_16x16x32_bf16 v[34:37], v[176:179], v[192:195], v[34:37]
	v_mfma_f32_16x16x32_bf16 v[22:25], v[168:171], v[204:207], v[22:25]
	v_mfma_f32_16x16x32_bf16 v[18:21], v[176:179], v[204:207], v[18:21]
	v_mfma_f32_16x16x32_bf16 v[6:9], v[168:171], v[212:215], v[6:9]
	v_mfma_f32_16x16x32_bf16 v[2:5], v[176:179], v[212:215], v[2:5]
	v_mfma_f32_16x16x32_bf16 v[54:57], v[172:175], v[188:191], v[54:57]
	v_mfma_f32_16x16x32_bf16 v[50:53], v[180:183], v[188:191], v[50:53]
	v_mfma_f32_16x16x32_bf16 v[38:41], v[172:175], v[196:199], v[38:41]
	v_mfma_f32_16x16x32_bf16 v[34:37], v[180:183], v[196:199], v[34:37]
	v_mfma_f32_16x16x32_bf16 v[22:25], v[172:175], v[208:211], v[22:25]
	v_mfma_f32_16x16x32_bf16 v[18:21], v[180:183], v[208:211], v[18:21]
	v_mfma_f32_16x16x32_bf16 v[6:9], v[172:175], v[216:219], v[6:9]
	v_mfma_f32_16x16x32_bf16 v[2:5], v[180:183], v[216:219], v[2:5]
	s_setprio 0
	s_barrier
	s_add_i32 s50, s50, 2
	s_add_u32 s24, s24, 0x100
	s_addc_u32 s25, s25, 0
	s_add_u32 s48, s48, 0x100
	s_addc_u32 s49, s49, 0
	s_cmp_gt_u32 s50, 29
	s_cbranch_scc0 .LBB0_203
	s_and_b64 vcc, exec, s[6:7]
	s_cbranch_vccz .LBB0_206
	s_barrier

.LBB0_285:
	ds_read_b128 v[130:133], v170
	ds_read_b128 v[134:137], v170 offset:1024
	ds_read_b128 v[138:141], v170 offset:2048
	ds_read_b128 v[142:145], v170 offset:3072
	ds_read_b128 v[158:161], v171
	ds_read_b128 v[162:165], v171 offset:1024
	ds_read_b128 v[174:177], v171 offset:2048
	ds_read_b128 v[178:181], v171 offset:3072
	s_add_u32 s26, s24, 0x100
	s_addc_u32 s27, s25, 0
	s_cmpk_eq_i32 s50, 0x54
	s_cselect_b32 s31, s3, s27
	s_cselect_b32 s30, s2, s26
	s_cselect_b32 s29, s23, s49
	s_cselect_b32 s28, s22, s48
	v_lshl_add_u64 v[166:167], s[24:25], 0, v[150:151]
	s_add_i32 m0, s33, 0xc000
	ds_read_b128 v[182:185], v172
	ds_read_b128 v[186:189], v172 offset:1024
	ds_read_b128 v[190:193], v172 offset:2048
	ds_read_b128 v[194:197], v172 offset:3072
	ds_read_b128 v[198:201], v172 offset:4096
	ds_read_b128 v[204:207], v172 offset:5120
	ds_read_b128 v[208:211], v172 offset:6144
	ds_read_b128 v[212:215], v172 offset:7168
	global_load_lds_dwordx4 v[166:167], off
	v_lshl_add_u64 v[166:167], s[24:25], 0, v[152:153]
	s_add_i32 m0, s33, 0xe000
	s_nop 0
	global_load_lds_dwordx4 v[166:167], off
	s_waitcnt vmcnt(8)
	s_waitcnt lgkmcnt(0)
	s_barrier
	s_setprio 1
	s_waitcnt lgkmcnt(0)
	v_mfma_f32_16x16x32_bf16 v[126:129], v[130:133], v[182:185], v[126:129]
	v_mfma_f32_16x16x32_bf16 v[122:125], v[138:141], v[182:185], v[122:125]
	v_mfma_f32_16x16x32_bf16 v[110:113], v[130:133], v[190:193], v[110:113]
	v_mfma_f32_16x16x32_bf16 v[106:109], v[138:141], v[190:193], v[106:109]
	v_mfma_f32_16x16x32_bf16 v[94:97], v[130:133], v[198:201], v[94:97]
	v_mfma_f32_16x16x32_bf16 v[90:93], v[138:141], v[198:201], v[90:93]
	v_mfma_f32_16x16x32_bf16 v[78:81], v[130:133], v[208:211], v[78:81]
	v_mfma_f32_16x16x32_bf16 v[74:77], v[138:141], v[208:211], v[74:77]
	v_mfma_f32_16x16x32_bf16 v[126:129], v[134:137], v[186:189], v[126:129]
	v_mfma_f32_16x16x32_bf16 v[122:125], v[142:145], v[186:189], v[122:125]
	v_mfma_f32_16x16x32_bf16 v[110:113], v[134:137], v[194:197], v[110:113]
	v_mfma_f32_16x16x32_bf16 v[106:109], v[142:145], v[194:197], v[106:109]
	v_mfma_f32_16x16x32_bf16 v[94:97], v[134:137], v[204:207], v[94:97]
	v_mfma_f32_16x16x32_bf16 v[90:93], v[142:145], v[204:207], v[90:93]
	v_mfma_f32_16x16x32_bf16 v[78:81], v[134:137], v[212:215], v[78:81]
	v_mfma_f32_16x16x32_bf16 v[74:77], v[142:145], v[212:215], v[74:77]
	v_mfma_f32_16x16x32_bf16 v[118:121], v[158:161], v[182:185], v[118:121]
	v_mfma_f32_16x16x32_bf16 v[114:117], v[174:177], v[182:185], v[114:117]
	v_mfma_f32_16x16x32_bf16 v[102:105], v[158:161], v[190:193], v[102:105]
	v_mfma_f32_16x16x32_bf16 v[98:101], v[174:177], v[190:193], v[98:101]
	v_mfma_f32_16x16x32_bf16 v[86:89], v[158:161], v[198:201], v[86:89]
	v_mfma_f32_16x16x32_bf16 v[82:85], v[174:177], v[198:201], v[82:85]
	v_mfma_f32_16x16x32_bf16 v[70:73], v[158:161], v[208:211], v[70:73]
	v_mfma_f32_16x16x32_bf16 v[66:69], v[174:177], v[208:211], v[66:69]
	v_mfma_f32_16x16x32_bf16 v[118:121], v[162:165], v[186:189], v[118:121]
	v_mfma_f32_16x16x32_bf16 v[114:117], v[178:181], v[186:189], v[114:117]
	v_mfma_f32_16x16x32_bf16 v[102:105], v[162:165], v[194:197], v[102:105]
	v_mfma_f32_16x16x32_bf16 v[98:101], v[178:181], v[194:197], v[98:101]
	v_mfma_f32_16x16x32_bf16 v[86:89], v[162:165], v[204:207], v[86:89]
	v_mfma_f32_16x16x32_bf16 v[82:85], v[178:181], v[204:207], v[82:85]
	v_mfma_f32_16x16x32_bf16 v[70:73], v[162:165], v[212:215], v[70:73]
	v_mfma_f32_16x16x32_bf16 v[66:69], v[178:181], v[212:215], v[66:69]
	s_setprio 0
	s_barrier
	s_add_i32 s24, s42, s17
	v_lshl_add_u64 v[166:167], s[28:29], 0, v[146:147]
	s_mov_b32 m0, s24
	ds_read_b128 v[182:185], v172 offset:16384
	ds_read_b128 v[186:189], v172 offset:17408
	ds_read_b128 v[190:193], v172 offset:18432
	ds_read_b128 v[194:197], v172 offset:19456
	ds_read_b128 v[198:201], v172 offset:20480
	ds_read_b128 v[204:207], v172 offset:21504
	ds_read_b128 v[208:211], v172 offset:22528
	ds_read_b128 v[212:215], v172 offset:23552
	global_load_lds_dwordx4 v[166:167], off
	s_add_i32 m0, s24, 0x2000
	s_add_u32 s24, s28, 0x160000
	v_lshl_add_u64 v[216:217], s[28:29], 0, v[148:149]
	s_addc_u32 s25, s29, 0
	s_add_i32 s51, s43, s17
	global_load_lds_dwordx4 v[216:217], off
	v_lshl_add_u64 v[218:219], s[24:25], 0, v[146:147]
	s_mov_b32 m0, s51
	v_lshl_add_u64 v[220:221], s[30:31], 0, v[148:149]
	global_load_lds_dwordx4 v[218:219], off
	v_lshl_add_u64 v[218:219], s[24:25], 0, v[148:149]
	s_add_i32 m0, s51, 0x2000
	s_nop 0
	global_load_lds_dwordx4 v[218:219], off
	v_lshl_add_u64 v[218:219], s[30:31], 0, v[146:147]
	s_mov_b32 m0, s33
	s_nop 0
	global_load_lds_dwordx4 v[218:219], off
	s_mov_b32 m0, s34
	s_nop 0
	global_load_lds_dwordx4 v[220:221], off
	s_waitcnt vmcnt(8)
	s_waitcnt lgkmcnt(0)
	s_barrier
	s_setprio 1
	s_waitcnt lgkmcnt(0)
	v_mfma_f32_16x16x32_bf16 v[62:65], v[130:133], v[182:185], v[62:65]
	v_mfma_f32_16x16x32_bf16 v[58:61], v[138:141], v[182:185], v[58:61]
	v_mfma_f32_16x16x32_bf16 v[46:49], v[130:133], v[190:193], v[46:49]
	v_mfma_f32_16x16x32_bf16 v[42:45], v[138:141], v[190:193], v[42:45]
	v_mfma_f32_16x16x32_bf16 v[30:33], v[130:133], v[198:201], v[30:33]
	v_mfma_f32_16x16x32_bf16 v[26:29], v[138:141], v[198:201], v[26:29]
	v_mfma_f32_16x16x32_bf16 v[14:17], v[130:133], v[208:211], v[14:17]
	v_mfma_f32_16x16x32_bf16 v[10:13], v[138:141], v[208:211], v[10:13]
	v_mfma_f32_16x16x32_bf16 v[62:65], v[134:137], v[186:189], v[62:65]
	v_mfma_f32_16x16x32_bf16 v[58:61], v[142:145], v[186:189], v[58:61]
	v_mfma_f32_16x16x32_bf16 v[46:49], v[134:137], v[194:197], v[46:49]
	v_mfma_f32_16x16x32_bf16 v[42:45], v[142:145], v[194:197], v[42:45]
	v_mfma_f32_16x16x32_bf16 v[30:33], v[134:137], v[204:207], v[30:33]
	v_mfma_f32_16x16x32_bf16 v[26:29], v[142:145], v[204:207], v[26:29]
	v_mfma_f32_16x16x32_bf16 v[14:17], v[134:137], v[212:215], v[14:17]
	v_mfma_f32_16x16x32_bf16 v[10:13], v[142:145], v[212:215], v[10:13]
	v_mfma_f32_16x16x32_bf16 v[54:57], v[158:161], v[182:185], v[54:57]
	v_mfma_f32_16x16x32_bf16 v[50:53], v[174:177], v[182:185], v[50:53]
	v_mfma_f32_16x16x32_bf16 v[38:41], v[158:161], v[190:193], v[38:41]
	v_mfma_f32_16x16x32_bf16 v[34:37], v[174:177], v[190:193], v[34:37]
	v_mfma_f32_16x16x32_bf16 v[22:25], v[158:161], v[198:201], v[22:25]
	v_mfma_f32_16x16x32_bf16 v[18:21], v[174:177], v[198:201], v[18:21]
	v_mfma_f32_16x16x32_bf16 v[6:9], v[158:161], v[208:211], v[6:9]
	v_mfma_f32_16x16x32_bf16 v[2:5], v[174:177], v[208:211], v[2:5]
	v_mfma_f32_16x16x32_bf16 v[54:57], v[162:165], v[186:189], v[54:57]
	v_mfma_f32_16x16x32_bf16 v[50:53], v[178:181], v[186:189], v[50:53]
	v_mfma_f32_16x16x32_bf16 v[38:41], v[162:165], v[194:197], v[38:41]
	v_mfma_f32_16x16x32_bf16 v[34:37], v[178:181], v[194:197], v[34:37]
	v_mfma_f32_16x16x32_bf16 v[22:25], v[162:165], v[204:207], v[22:25]
	v_mfma_f32_16x16x32_bf16 v[18:21], v[178:181], v[204:207], v[18:21]
	v_mfma_f32_16x16x32_bf16 v[6:9], v[162:165], v[212:215], v[6:9]
	v_mfma_f32_16x16x32_bf16 v[2:5], v[178:181], v[212:215], v[2:5]
	s_setprio 0
	s_barrier
	s_add_i32 s51, 0, 0x18000
	s_add_i32 s52, 0, 0x1c000
	v_add_u32_e32 v142, s51, v168
	v_add_u32_e32 v178, s52, v168
	ds_read_b128 v[130:133], v142
	ds_read_b128 v[134:137], v142 offset:1024
	ds_read_b128 v[138:141], v142 offset:2048
	ds_read_b128 v[142:145], v142 offset:3072
	ds_read_b128 v[158:161], v178
	ds_read_b128 v[162:165], v178 offset:1024
	ds_read_b128 v[174:177], v178 offset:2048
	ds_read_b128 v[178:181], v178 offset:3072
	s_add_u32 s24, s30, 0x160000
	s_addc_u32 s25, s31, 0
	s_mov_b32 m0, s35
	v_lshl_add_u64 v[222:223], s[24:25], 0, v[146:147]
	ds_read_b128 v[182:185], v172 offset:32768
	ds_read_b128 v[186:189], v172 offset:33792
	ds_read_b128 v[190:193], v172 offset:34816
	ds_read_b128 v[194:197], v172 offset:35840
	ds_read_b128 v[198:201], v172 offset:36864
	ds_read_b128 v[204:207], v172 offset:37888
	ds_read_b128 v[208:211], v172 offset:38912
	ds_read_b128 v[212:215], v172 offset:39936
	global_load_lds_dwordx4 v[222:223], off
	v_lshl_add_u64 v[222:223], s[24:25], 0, v[148:149]
	s_mov_b32 m0, s36
	s_nop 0
	global_load_lds_dwordx4 v[222:223], off
	s_waitcnt vmcnt(8)
	s_waitcnt lgkmcnt(0)
	s_barrier
	s_setprio 1
	s_waitcnt lgkmcnt(0)
	v_mfma_f32_16x16x32_bf16 v[126:129], v[130:133], v[182:185], v[126:129]
	v_mfma_f32_16x16x32_bf16 v[122:125], v[138:141], v[182:185], v[122:125]
	v_mfma_f32_16x16x32_bf16 v[110:113], v[130:133], v[190:193], v[110:113]
	v_mfma_f32_16x16x32_bf16 v[106:109], v[138:141], v[190:193], v[106:109]
	v_mfma_f32_16x16x32_bf16 v[94:97], v[130:133], v[198:201], v[94:97]
	v_mfma_f32_16x16x32_bf16 v[90:93], v[138:141], v[198:201], v[90:93]
	v_mfma_f32_16x16x32_bf16 v[78:81], v[130:133], v[208:211], v[78:81]
	v_mfma_f32_16x16x32_bf16 v[74:77], v[138:141], v[208:211], v[74:77]
	v_mfma_f32_16x16x32_bf16 v[126:129], v[134:137], v[186:189], v[126:129]
	v_mfma_f32_16x16x32_bf16 v[122:125], v[142:145], v[186:189], v[122:125]
	v_mfma_f32_16x16x32_bf16 v[110:113], v[134:137], v[194:197], v[110:113]
	v_mfma_f32_16x16x32_bf16 v[106:109], v[142:145], v[194:197], v[106:109]
	v_mfma_f32_16x16x32_bf16 v[94:97], v[134:137], v[204:207], v[94:97]
	v_mfma_f32_16x16x32_bf16 v[90:93], v[142:145], v[204:207], v[90:93]
	v_mfma_f32_16x16x32_bf16 v[78:81], v[134:137], v[212:215], v[78:81]
	v_mfma_f32_16x16x32_bf16 v[74:77], v[142:145], v[212:215], v[74:77]
	v_mfma_f32_16x16x32_bf16 v[118:121], v[158:161], v[182:185], v[118:121]
	v_mfma_f32_16x16x32_bf16 v[114:117], v[174:177], v[182:185], v[114:117]
	v_mfma_f32_16x16x32_bf16 v[102:105], v[158:161], v[190:193], v[102:105]
	v_mfma_f32_16x16x32_bf16 v[98:101], v[174:177], v[190:193], v[98:101]
	v_mfma_f32_16x16x32_bf16 v[86:89], v[158:161], v[198:201], v[86:89]
	v_mfma_f32_16x16x32_bf16 v[82:85], v[174:177], v[198:201], v[82:85]
	v_mfma_f32_16x16x32_bf16 v[70:73], v[158:161], v[208:211], v[70:73]
	v_mfma_f32_16x16x32_bf16 v[66:69], v[174:177], v[208:211], v[66:69]
	v_mfma_f32_16x16x32_bf16 v[118:121], v[162:165], v[186:189], v[118:121]
	v_mfma_f32_16x16x32_bf16 v[114:117], v[178:181], v[186:189], v[114:117]
	v_mfma_f32_16x16x32_bf16 v[102:105], v[162:165], v[194:197], v[102:105]
	v_mfma_f32_16x16x32_bf16 v[98:101], v[178:181], v[194:197], v[98:101]
	v_mfma_f32_16x16x32_bf16 v[86:89], v[162:165], v[204:207], v[86:89]
	v_mfma_f32_16x16x32_bf16 v[82:85], v[178:181], v[204:207], v[82:85]
	v_mfma_f32_16x16x32_bf16 v[70:73], v[162:165], v[212:215], v[70:73]
	v_mfma_f32_16x16x32_bf16 v[66:69], v[178:181], v[212:215], v[66:69]
	s_setprio 0
	s_barrier
	s_add_i32 s24, s51, s17
	v_lshl_add_u64 v[166:167], v[166:167], 0, s[8:9]
	s_mov_b32 m0, s24
	ds_read_b128 v[182:185], v172 offset:49152
	ds_read_b128 v[186:189], v172 offset:50176
	ds_read_b128 v[190:193], v172 offset:51200
	ds_read_b128 v[194:197], v172 offset:52224
	ds_read_b128 v[198:201], v172 offset:53248
	ds_read_b128 v[204:207], v172 offset:54272
	ds_read_b128 v[208:211], v172 offset:55296
	ds_read_b128 v[212:215], v172 offset:56320
	global_load_lds_dwordx4 v[166:167], off
	s_add_i32 m0, s24, 0x2000
	s_add_u32 s24, s28, 0x160080
	v_lshl_add_u64 v[166:167], v[216:217], 0, s[8:9]
	s_addc_u32 s25, s29, 0
	s_add_i32 s28, s52, s17
	global_load_lds_dwordx4 v[166:167], off
	v_lshl_add_u64 v[166:167], s[24:25], 0, v[146:147]
	s_mov_b32 m0, s28
	s_nop 0
	global_load_lds_dwordx4 v[166:167], off
	v_lshl_add_u64 v[166:167], s[24:25], 0, v[148:149]
	s_add_i32 m0, s28, 0x2000
	s_nop 0
	global_load_lds_dwordx4 v[166:167], off
	v_lshl_add_u64 v[166:167], v[218:219], 0, s[8:9]
	s_mov_b32 m0, s38
	s_nop 0
	global_load_lds_dwordx4 v[166:167], off
	v_lshl_add_u64 v[166:167], v[220:221], 0, s[8:9]
	s_mov_b32 m0, s39
	s_nop 0
	global_load_lds_dwordx4 v[166:167], off
	s_waitcnt vmcnt(8)
	s_waitcnt lgkmcnt(0)
	s_barrier
	s_setprio 1
	s_waitcnt lgkmcnt(0)
	v_mfma_f32_16x16x32_bf16 v[62:65], v[130:133], v[182:185], v[62:65]
	v_mfma_f32_16x16x32_bf16 v[58:61], v[138:141], v[182:185], v[58:61]
	v_mfma_f32_16x16x32_bf16 v[46:49], v[130:133], v[190:193], v[46:49]
	v_mfma_f32_16x16x32_bf16 v[42:45], v[138:141], v[190:193], v[42:45]
	v_mfma_f32_16x16x32_bf16 v[30:33], v[130:133], v[198:201], v[30:33]
	v_mfma_f32_16x16x32_bf16 v[26:29], v[138:141], v[198:201], v[26:29]
	v_mfma_f32_16x16x32_bf16 v[14:17], v[130:133], v[208:211], v[14:17]
	v_mfma_f32_16x16x32_bf16 v[10:13], v[138:141], v[208:211], v[10:13]
	v_mfma_f32_16x16x32_bf16 v[62:65], v[134:137], v[186:189], v[62:65]
	v_mfma_f32_16x16x32_bf16 v[58:61], v[142:145], v[186:189], v[58:61]
	v_mfma_f32_16x16x32_bf16 v[46:49], v[134:137], v[194:197], v[46:49]
	v_mfma_f32_16x16x32_bf16 v[42:45], v[142:145], v[194:197], v[42:45]
	v_mfma_f32_16x16x32_bf16 v[30:33], v[134:137], v[204:207], v[30:33]
	v_mfma_f32_16x16x32_bf16 v[26:29], v[142:145], v[204:207], v[26:29]
	v_mfma_f32_16x16x32_bf16 v[14:17], v[134:137], v[212:215], v[14:17]
	v_mfma_f32_16x16x32_bf16 v[10:13], v[142:145], v[212:215], v[10:13]
	v_mfma_f32_16x16x32_bf16 v[54:57], v[158:161], v[182:185], v[54:57]
	v_mfma_f32_16x16x32_bf16 v[50:53], v[174:177], v[182:185], v[50:53]
	v_mfma_f32_16x16x32_bf16 v[38:41], v[158:161], v[190:193], v[38:41]
	v_mfma_f32_16x16x32_bf16 v[34:37], v[174:177], v[190:193], v[34:37]
	v_mfma_f32_16x16x32_bf16 v[22:25], v[158:161], v[198:201], v[22:25]
	v_mfma_f32_16x16x32_bf16 v[18:21], v[174:177], v[198:201], v[18:21]
	v_mfma_f32_16x16x32_bf16 v[6:9], v[158:161], v[208:211], v[6:9]
	v_mfma_f32_16x16x32_bf16 v[2:5], v[174:177], v[208:211], v[2:5]
	v_mfma_f32_16x16x32_bf16 v[54:57], v[162:165], v[186:189], v[54:57]
	v_mfma_f32_16x16x32_bf16 v[50:53], v[178:181], v[186:189], v[50:53]
	v_mfma_f32_16x16x32_bf16 v[38:41], v[162:165], v[194:197], v[38:41]
	v_mfma_f32_16x16x32_bf16 v[34:37], v[178:181], v[194:197], v[34:37]
	v_mfma_f32_16x16x32_bf16 v[22:25], v[162:165], v[204:207], v[22:25]
	v_mfma_f32_16x16x32_bf16 v[18:21], v[178:181], v[204:207], v[18:21]
	v_mfma_f32_16x16x32_bf16 v[6:9], v[162:165], v[212:215], v[6:9]
	v_mfma_f32_16x16x32_bf16 v[2:5], v[178:181], v[212:215], v[2:5]
	s_setprio 0
	s_barrier
	s_add_i32 s50, s50, 2
	s_add_u32 s48, s48, 0x100
	s_addc_u32 s49, s49, 0
	s_cmpk_gt_u32 s50, 0x55
	s_mov_b64 s[24:25], s[26:27]
	s_cbranch_scc0 .LBB0_285
	s_and_b64 vcc, exec, s[10:11]
	s_cbranch_vccz .LBB0_288
	s_barrier

.LBB0_387:
	ds_read_b128 v[18:21], v219
	ds_read_b128 v[22:25], v219 offset:1024
	ds_read_b128 v[26:29], v219 offset:2048
	ds_read_b128 v[30:33], v219 offset:3072
	ds_read_b128 v[34:37], v220
	ds_read_b128 v[38:41], v220 offset:1024
	ds_read_b128 v[42:45], v220 offset:2048
	ds_read_b128 v[46:49], v220 offset:3072
	s_add_u32 s10, s2, 0xfff80080
	s_addc_u32 s11, s3, -1
	s_cmp_eq_u32 s23, 28
	s_cselect_b32 s13, s1, s11
	s_cselect_b32 s12, s15, s10
	s_cselect_b32 s11, s16, s19
	s_cselect_b32 s10, s17, s18
	v_lshl_add_u64 v[200:201], s[2:3], 0, v[192:193]
	s_add_i32 m0, s47, 0xc000
	ds_read_b128 v[114:117], v221
	ds_read_b128 v[150:153], v221 offset:1024
	ds_read_b128 v[170:173], v221 offset:2048
	ds_read_b128 v[174:177], v221 offset:3072
	ds_read_b128 v[178:181], v221 offset:4096
	ds_read_b128 v[228:231], v221 offset:5120
	ds_read_b128 v[232:235], v221 offset:6144
	ds_read_b128 v[236:239], v221 offset:7168
	global_load_lds_dwordx4 v[200:201], off
	v_lshl_add_u64 v[200:201], s[2:3], 0, v[194:195]
	s_add_i32 m0, s47, 0xe000
	s_nop 0
	global_load_lds_dwordx4 v[200:201], off
	s_waitcnt vmcnt(8)
	s_waitcnt lgkmcnt(0)
	s_barrier
	s_setprio 1
	s_waitcnt lgkmcnt(0)
	v_mfma_f32_16x16x32_bf16 v[166:169], v[18:21], v[114:117], v[166:169]
	v_mfma_f32_16x16x32_bf16 v[162:165], v[26:29], v[114:117], v[162:165]
	v_mfma_f32_16x16x32_bf16 v[146:149], v[18:21], v[170:173], v[146:149]
	v_mfma_f32_16x16x32_bf16 v[142:145], v[26:29], v[170:173], v[142:145]
	v_mfma_f32_16x16x32_bf16 v[130:133], v[18:21], v[178:181], v[130:133]
	v_mfma_f32_16x16x32_bf16 v[126:129], v[26:29], v[178:181], v[126:129]
	v_mfma_f32_16x16x32_bf16 v[110:113], v[18:21], v[232:235], v[110:113]
	v_mfma_f32_16x16x32_bf16 v[106:109], v[26:29], v[232:235], v[106:109]
	v_mfma_f32_16x16x32_bf16 v[166:169], v[22:25], v[150:153], v[166:169]
	v_mfma_f32_16x16x32_bf16 v[162:165], v[30:33], v[150:153], v[162:165]
	v_mfma_f32_16x16x32_bf16 v[146:149], v[22:25], v[174:177], v[146:149]
	v_mfma_f32_16x16x32_bf16 v[142:145], v[30:33], v[174:177], v[142:145]
	v_mfma_f32_16x16x32_bf16 v[130:133], v[22:25], v[228:231], v[130:133]
	v_mfma_f32_16x16x32_bf16 v[126:129], v[30:33], v[228:231], v[126:129]
	v_mfma_f32_16x16x32_bf16 v[110:113], v[22:25], v[236:239], v[110:113]
	v_mfma_f32_16x16x32_bf16 v[106:109], v[30:33], v[236:239], v[106:109]
	v_mfma_f32_16x16x32_bf16 v[158:161], v[34:37], v[114:117], v[158:161]
	v_mfma_f32_16x16x32_bf16 v[138:141], v[34:37], v[170:173], v[138:141]
	v_mfma_f32_16x16x32_bf16 v[134:137], v[42:45], v[170:173], v[134:137]
	v_mfma_f32_16x16x32_bf16 v[122:125], v[34:37], v[178:181], v[122:125]
	v_mfma_f32_16x16x32_bf16 v[118:121], v[42:45], v[178:181], v[118:121]
	v_mfma_f32_16x16x32_bf16 v[102:105], v[34:37], v[232:235], v[102:105]
	v_mfma_f32_16x16x32_bf16 v[98:101], v[42:45], v[232:235], v[98:101]
	v_mfma_f32_16x16x32_bf16 v[158:161], v[38:41], v[150:153], v[158:161]
	v_mfma_f32_16x16x32_bf16 v[114:117], v[42:45], v[114:117], v[154:157]
	v_mfma_f32_16x16x32_bf16 v[138:141], v[38:41], v[174:177], v[138:141]
	v_mfma_f32_16x16x32_bf16 v[134:137], v[46:49], v[174:177], v[134:137]
	v_mfma_f32_16x16x32_bf16 v[122:125], v[38:41], v[228:231], v[122:125]
	v_mfma_f32_16x16x32_bf16 v[118:121], v[46:49], v[228:231], v[118:121]
	v_mfma_f32_16x16x32_bf16 v[102:105], v[38:41], v[236:239], v[102:105]
	v_mfma_f32_16x16x32_bf16 v[98:101], v[46:49], v[236:239], v[98:101]
	v_mfma_f32_16x16x32_bf16 v[114:117], v[46:49], v[150:153], v[114:117]
	s_setprio 0
	s_barrier
	s_add_i32 s33, s84, s43
	v_lshl_add_u64 v[200:201], s[10:11], 0, v[182:183]
	s_mov_b32 m0, s33
	ds_read_b128 v[150:153], v221 offset:16384
	ds_read_b128 v[154:157], v221 offset:17408
	ds_read_b128 v[170:173], v221 offset:18432
	ds_read_b128 v[174:177], v221 offset:19456
	ds_read_b128 v[178:181], v221 offset:20480
	ds_read_b128 v[228:231], v221 offset:21504
	ds_read_b128 v[232:235], v221 offset:22528
	ds_read_b128 v[236:239], v221 offset:23552
	global_load_lds_dwordx4 v[200:201], off
	s_add_i32 m0, s33, 0x2000
	s_add_u32 s60, s10, 0x80000
	v_lshl_add_u64 v[248:249], s[10:11], 0, v[184:185]
	s_addc_u32 s61, s11, 0
	s_add_i32 s33, s85, s43
	global_load_lds_dwordx4 v[248:249], off
	v_lshl_add_u64 v[240:241], s[60:61], 0, v[182:183]
	s_mov_b32 m0, s33
	v_lshl_add_u64 v[250:251], s[12:13], 0, v[182:183]
	global_load_lds_dwordx4 v[240:241], off
	v_lshl_add_u64 v[240:241], s[60:61], 0, v[184:185]
	s_add_i32 m0, s33, 0x2000
	v_lshl_add_u64 v[210:211], s[12:13], 0, v[184:185]
	global_load_lds_dwordx4 v[240:241], off
	s_mov_b32 m0, s47
	s_nop 0
	global_load_lds_dwordx4 v[250:251], off
	s_mov_b32 m0, s51
	s_nop 0
	global_load_lds_dwordx4 v[210:211], off
	s_waitcnt vmcnt(8)
	s_waitcnt lgkmcnt(0)
	s_barrier
	s_setprio 1
	s_waitcnt lgkmcnt(0)
	v_mfma_f32_16x16x32_bf16 v[94:97], v[18:21], v[150:153], v[94:97]
	v_mfma_f32_16x16x32_bf16 v[90:93], v[26:29], v[150:153], v[90:93]
	v_mfma_f32_16x16x32_bf16 v[78:81], v[18:21], v[170:173], v[78:81]
	v_mfma_f32_16x16x32_bf16 v[74:77], v[26:29], v[170:173], v[74:77]
	v_mfma_f32_16x16x32_bf16 v[62:65], v[18:21], v[178:181], v[62:65]
	v_mfma_f32_16x16x32_bf16 v[58:61], v[26:29], v[178:181], v[58:61]
	v_mfma_f32_16x16x32_bf16 v[14:17], v[18:21], v[232:235], v[14:17]
	v_mfma_f32_16x16x32_bf16 v[10:13], v[26:29], v[232:235], v[10:13]
	v_mfma_f32_16x16x32_bf16 v[94:97], v[22:25], v[154:157], v[94:97]
	v_mfma_f32_16x16x32_bf16 v[90:93], v[30:33], v[154:157], v[90:93]
	v_mfma_f32_16x16x32_bf16 v[78:81], v[22:25], v[174:177], v[78:81]
	v_mfma_f32_16x16x32_bf16 v[74:77], v[30:33], v[174:177], v[74:77]
	v_mfma_f32_16x16x32_bf16 v[62:65], v[22:25], v[228:231], v[62:65]
	v_mfma_f32_16x16x32_bf16 v[58:61], v[30:33], v[228:231], v[58:61]
	v_mfma_f32_16x16x32_bf16 v[14:17], v[22:25], v[236:239], v[14:17]
	v_mfma_f32_16x16x32_bf16 v[10:13], v[30:33], v[236:239], v[10:13]
	v_mfma_f32_16x16x32_bf16 v[54:57], v[34:37], v[178:181], v[54:57]
	v_mfma_f32_16x16x32_bf16 v[50:53], v[42:45], v[178:181], v[50:53]
	v_mfma_f32_16x16x32_bf16 v[6:9], v[34:37], v[232:235], v[6:9]
	v_mfma_f32_16x16x32_bf16 v[2:5], v[42:45], v[232:235], v[2:5]
	v_mfma_f32_16x16x32_bf16 v[18:21], v[34:37], v[150:153], v[86:89]
	v_mfma_f32_16x16x32_bf16 v[22:25], v[42:45], v[150:153], v[82:85]
	v_mfma_f32_16x16x32_bf16 v[26:29], v[34:37], v[170:173], v[70:73]
	v_mfma_f32_16x16x32_bf16 v[30:33], v[42:45], v[170:173], v[66:69]
	v_mfma_f32_16x16x32_bf16 v[54:57], v[38:41], v[228:231], v[54:57]
	v_mfma_f32_16x16x32_bf16 v[50:53], v[46:49], v[228:231], v[50:53]
	v_mfma_f32_16x16x32_bf16 v[6:9], v[38:41], v[236:239], v[6:9]
	v_mfma_f32_16x16x32_bf16 v[2:5], v[46:49], v[236:239], v[2:5]
	v_mfma_f32_16x16x32_bf16 v[18:21], v[38:41], v[154:157], v[18:21]
	v_mfma_f32_16x16x32_bf16 v[22:25], v[46:49], v[154:157], v[22:25]
	v_mfma_f32_16x16x32_bf16 v[26:29], v[38:41], v[174:177], v[26:29]
	v_mfma_f32_16x16x32_bf16 v[30:33], v[46:49], v[174:177], v[30:33]
	s_setprio 0
	s_barrier
	s_add_i32 s33, 0, 0x18000
	s_add_i32 s46, 0, 0x1c000
	v_add_u32_e32 v46, s33, v204
	v_add_u32_e32 v66, s46, v204
	ds_read_b128 v[34:37], v46
	ds_read_b128 v[38:41], v46 offset:1024
	ds_read_b128 v[42:45], v46 offset:2048
	ds_read_b128 v[46:49], v46 offset:3072
	ds_read_b128 v[150:153], v66
	ds_read_b128 v[170:173], v66 offset:1024
	ds_read_b128 v[174:177], v66 offset:2048
	ds_read_b128 v[178:181], v66 offset:3072
	s_add_u32 s12, s12, 0x80000
	s_addc_u32 s13, s13, 0
	s_mov_b32 m0, s74
	v_lshl_add_u64 v[154:155], s[12:13], 0, v[182:183]
	ds_read_b128 v[66:69], v221 offset:32768
	ds_read_b128 v[70:73], v221 offset:33792
	ds_read_b128 v[82:85], v221 offset:34816
	ds_read_b128 v[86:89], v221 offset:35840
	ds_read_b128 v[228:231], v221 offset:36864
	ds_read_b128 v[232:235], v221 offset:37888
	ds_read_b128 v[236:239], v221 offset:38912
	ds_read_b128 v[240:243], v221 offset:39936
	global_load_lds_dwordx4 v[154:155], off
	v_lshl_add_u64 v[154:155], s[12:13], 0, v[184:185]
	s_mov_b32 m0, s75
	s_nop 0
	global_load_lds_dwordx4 v[154:155], off
	s_waitcnt vmcnt(8)
	s_waitcnt lgkmcnt(0)
	s_barrier
	s_setprio 1
	s_waitcnt lgkmcnt(0)
	v_mfma_f32_16x16x32_bf16 v[154:157], v[34:37], v[66:69], v[166:169]
	v_mfma_f32_16x16x32_bf16 v[166:169], v[38:41], v[70:73], v[154:157]
	v_mfma_f32_16x16x32_bf16 v[154:157], v[42:45], v[66:69], v[162:165]
	v_mfma_f32_16x16x32_bf16 v[146:149], v[34:37], v[82:85], v[146:149]
	v_mfma_f32_16x16x32_bf16 v[142:145], v[42:45], v[82:85], v[142:145]
	v_mfma_f32_16x16x32_bf16 v[130:133], v[34:37], v[228:231], v[130:133]
	v_mfma_f32_16x16x32_bf16 v[126:129], v[42:45], v[228:231], v[126:129]
	v_mfma_f32_16x16x32_bf16 v[110:113], v[34:37], v[236:239], v[110:113]
	v_mfma_f32_16x16x32_bf16 v[106:109], v[42:45], v[236:239], v[106:109]
	v_mfma_f32_16x16x32_bf16 v[162:165], v[46:49], v[70:73], v[154:157]
	v_mfma_f32_16x16x32_bf16 v[146:149], v[38:41], v[86:89], v[146:149]
	v_mfma_f32_16x16x32_bf16 v[142:145], v[46:49], v[86:89], v[142:145]
	v_mfma_f32_16x16x32_bf16 v[130:133], v[38:41], v[232:235], v[130:133]
	v_mfma_f32_16x16x32_bf16 v[126:129], v[46:49], v[232:235], v[126:129]
	v_mfma_f32_16x16x32_bf16 v[110:113], v[38:41], v[240:243], v[110:113]
	v_mfma_f32_16x16x32_bf16 v[106:109], v[46:49], v[240:243], v[106:109]
	v_mfma_f32_16x16x32_bf16 v[154:157], v[150:153], v[66:69], v[158:161]
	v_mfma_f32_16x16x32_bf16 v[66:69], v[174:177], v[66:69], v[114:117]
	v_mfma_f32_16x16x32_bf16 v[158:161], v[170:173], v[70:73], v[154:157]
	v_mfma_f32_16x16x32_bf16 v[154:157], v[178:181], v[70:73], v[66:69]
	v_mfma_f32_16x16x32_bf16 v[66:69], v[150:153], v[82:85], v[138:141]
	v_mfma_f32_16x16x32_bf16 v[138:141], v[170:173], v[86:89], v[66:69]
	v_mfma_f32_16x16x32_bf16 v[66:69], v[174:177], v[82:85], v[134:137]
	v_mfma_f32_16x16x32_bf16 v[134:137], v[178:181], v[86:89], v[66:69]
	v_mfma_f32_16x16x32_bf16 v[66:69], v[150:153], v[228:231], v[122:125]
	v_mfma_f32_16x16x32_bf16 v[122:125], v[170:173], v[232:235], v[66:69]
	v_mfma_f32_16x16x32_bf16 v[66:69], v[174:177], v[228:231], v[118:121]
	v_mfma_f32_16x16x32_bf16 v[118:121], v[178:181], v[232:235], v[66:69]
	v_mfma_f32_16x16x32_bf16 v[66:69], v[150:153], v[236:239], v[102:105]
	v_mfma_f32_16x16x32_bf16 v[102:105], v[170:173], v[240:243], v[66:69]
	v_mfma_f32_16x16x32_bf16 v[66:69], v[174:177], v[236:239], v[98:101]
	v_mfma_f32_16x16x32_bf16 v[98:101], v[178:181], v[240:243], v[66:69]
	s_setprio 0
	s_barrier
	s_add_i32 s12, s33, s43
	v_lshl_add_u64 v[82:83], v[200:201], 0, s[28:29]
	s_mov_b32 m0, s12
	s_nop 1
	ds_read_b128 v[66:69], v221 offset:49152
	ds_read_b128 v[70:73], v221 offset:50176
	ds_read_b128 v[114:117], v221 offset:51200
	ds_read_b128 v[228:231], v221 offset:52224
	ds_read_b128 v[232:235], v221 offset:53248
	ds_read_b128 v[236:239], v221 offset:54272
	ds_read_b128 v[240:243], v221 offset:55296
	ds_read_b128 v[244:247], v221 offset:56320
	global_load_lds_dwordx4 v[82:83], off
	s_add_i32 m0, s12, 0x2000
	s_add_u32 s10, s10, 0x80080
	v_lshl_add_u64 v[82:83], v[248:249], 0, s[28:29]
	s_addc_u32 s11, s11, 0
	s_add_i32 s12, s46, s43
	global_load_lds_dwordx4 v[82:83], off
	v_lshl_add_u64 v[82:83], s[10:11], 0, v[182:183]
	s_mov_b32 m0, s12
	s_nop 0
	global_load_lds_dwordx4 v[82:83], off
	v_lshl_add_u64 v[82:83], s[10:11], 0, v[184:185]
	s_add_i32 m0, s12, 0x2000
	s_nop 0
	global_load_lds_dwordx4 v[82:83], off
	v_lshl_add_u64 v[82:83], v[250:251], 0, s[28:29]
	s_mov_b32 m0, s77
	s_nop 0
	global_load_lds_dwordx4 v[82:83], off
	v_lshl_add_u64 v[82:83], v[210:211], 0, s[28:29]
	s_mov_b32 m0, s78
	s_nop 0
	global_load_lds_dwordx4 v[82:83], off
	s_waitcnt vmcnt(8)
	s_waitcnt lgkmcnt(0)
	s_barrier
	s_setprio 1
	s_waitcnt lgkmcnt(0)
	v_mfma_f32_16x16x32_bf16 v[82:85], v[34:37], v[66:69], v[94:97]
	v_mfma_f32_16x16x32_bf16 v[94:97], v[38:41], v[70:73], v[82:85]
	v_mfma_f32_16x16x32_bf16 v[82:85], v[42:45], v[66:69], v[90:93]
	v_mfma_f32_16x16x32_bf16 v[78:81], v[34:37], v[114:117], v[78:81]
	v_mfma_f32_16x16x32_bf16 v[74:77], v[42:45], v[114:117], v[74:77]
	v_mfma_f32_16x16x32_bf16 v[62:65], v[34:37], v[232:235], v[62:65]
	v_mfma_f32_16x16x32_bf16 v[58:61], v[42:45], v[232:235], v[58:61]
	v_mfma_f32_16x16x32_bf16 v[14:17], v[34:37], v[240:243], v[14:17]
	v_mfma_f32_16x16x32_bf16 v[10:13], v[42:45], v[240:243], v[10:13]
	v_mfma_f32_16x16x32_bf16 v[90:93], v[46:49], v[70:73], v[82:85]
	v_mfma_f32_16x16x32_bf16 v[78:81], v[38:41], v[228:231], v[78:81]
	v_mfma_f32_16x16x32_bf16 v[74:77], v[46:49], v[228:231], v[74:77]
	v_mfma_f32_16x16x32_bf16 v[62:65], v[38:41], v[236:239], v[62:65]
	v_mfma_f32_16x16x32_bf16 v[58:61], v[46:49], v[236:239], v[58:61]
	v_mfma_f32_16x16x32_bf16 v[14:17], v[38:41], v[244:247], v[14:17]
	v_mfma_f32_16x16x32_bf16 v[10:13], v[46:49], v[244:247], v[10:13]
	v_mfma_f32_16x16x32_bf16 v[18:21], v[150:153], v[66:69], v[18:21]
	v_mfma_f32_16x16x32_bf16 v[86:89], v[170:173], v[70:73], v[18:21]
	v_mfma_f32_16x16x32_bf16 v[18:21], v[174:177], v[66:69], v[22:25]
	v_mfma_f32_16x16x32_bf16 v[82:85], v[178:181], v[70:73], v[18:21]
	v_mfma_f32_16x16x32_bf16 v[18:21], v[150:153], v[114:117], v[26:29]
	v_mfma_f32_16x16x32_bf16 v[70:73], v[170:173], v[228:231], v[18:21]
	v_mfma_f32_16x16x32_bf16 v[18:21], v[174:177], v[114:117], v[30:33]
	v_mfma_f32_16x16x32_bf16 v[66:69], v[178:181], v[228:231], v[18:21]
	v_mfma_f32_16x16x32_bf16 v[18:21], v[150:153], v[232:235], v[54:57]
	v_mfma_f32_16x16x32_bf16 v[54:57], v[170:173], v[236:239], v[18:21]
	v_mfma_f32_16x16x32_bf16 v[18:21], v[174:177], v[232:235], v[50:53]
	v_mfma_f32_16x16x32_bf16 v[6:9], v[150:153], v[240:243], v[6:9]
	v_mfma_f32_16x16x32_bf16 v[2:5], v[174:177], v[240:243], v[2:5]
	v_mfma_f32_16x16x32_bf16 v[50:53], v[178:181], v[236:239], v[18:21]
	v_mfma_f32_16x16x32_bf16 v[6:9], v[170:173], v[244:247], v[6:9]
	v_mfma_f32_16x16x32_bf16 v[2:5], v[178:181], v[244:247], v[2:5]
	s_setprio 0
	s_barrier
	s_add_i32 s23, s23, 2
	s_add_u32 s2, s2, 0x100
	s_addc_u32 s3, s3, 0
	s_add_u32 s18, s18, 0x100
	s_addc_u32 s19, s19, 0
	s_cmp_gt_u32 s23, 29
	s_cbranch_scc0 .LBB0_387
	s_and_b64 vcc, exec, s[30:31]
	s_cbranch_vccz .LBB0_390
	s_barrier

.LBB0_1966:
	ds_read_b128 v[130:133], v169
	ds_read_b128 v[134:137], v169 offset:1024
	ds_read_b128 v[154:157], v169 offset:2048
	ds_read_b128 v[158:161], v169 offset:3072
	ds_read_b128 v[172:175], v170
	ds_read_b128 v[176:179], v170 offset:1024
	ds_read_b128 v[180:183], v170 offset:2048
	ds_read_b128 v[184:187], v170 offset:3072
	s_add_u32 s30, s28, 0xfff80080
	s_addc_u32 s31, s29, -1
	s_cmp_eq_u32 s51, 28
	s_cselect_b32 s35, s19, s31
	s_cselect_b32 s34, s25, s30
	s_cselect_b32 s31, s17, s50
	s_cselect_b32 s30, s27, s49
	v_lshl_add_u64 v[200:201], s[28:29], 0, v[146:147]
	s_add_i32 m0, s36, 0xc000
	ds_read_b128 v[188:191], v171
	ds_read_b128 v[192:195], v171 offset:1024
	ds_read_b128 v[196:199], v171 offset:2048
	ds_read_b128 v[204:207], v171 offset:3072
	ds_read_b128 v[208:211], v171 offset:4096
	ds_read_b128 v[212:215], v171 offset:5120
	ds_read_b128 v[216:219], v171 offset:6144
	ds_read_b128 v[220:223], v171 offset:7168
	global_load_lds_dwordx4 v[200:201], off
	v_lshl_add_u64 v[200:201], s[28:29], 0, v[148:149]
	s_add_i32 m0, s36, 0xe000
	s_nop 0
	global_load_lds_dwordx4 v[200:201], off
	s_waitcnt vmcnt(8)
	s_waitcnt lgkmcnt(0)
	s_barrier
	s_setprio 1
	s_waitcnt lgkmcnt(0)
	v_mfma_f32_16x16x32_bf16 v[126:129], v[130:133], v[188:191], v[126:129]
	v_mfma_f32_16x16x32_bf16 v[122:125], v[154:157], v[188:191], v[122:125]
	v_mfma_f32_16x16x32_bf16 v[110:113], v[130:133], v[196:199], v[110:113]
	v_mfma_f32_16x16x32_bf16 v[106:109], v[154:157], v[196:199], v[106:109]
	v_mfma_f32_16x16x32_bf16 v[94:97], v[130:133], v[208:211], v[94:97]
	v_mfma_f32_16x16x32_bf16 v[90:93], v[154:157], v[208:211], v[90:93]
	v_mfma_f32_16x16x32_bf16 v[78:81], v[130:133], v[216:219], v[78:81]
	v_mfma_f32_16x16x32_bf16 v[74:77], v[154:157], v[216:219], v[74:77]
	v_mfma_f32_16x16x32_bf16 v[126:129], v[134:137], v[192:195], v[126:129]
	v_mfma_f32_16x16x32_bf16 v[122:125], v[158:161], v[192:195], v[122:125]
	v_mfma_f32_16x16x32_bf16 v[110:113], v[134:137], v[204:207], v[110:113]
	v_mfma_f32_16x16x32_bf16 v[106:109], v[158:161], v[204:207], v[106:109]
	v_mfma_f32_16x16x32_bf16 v[94:97], v[134:137], v[212:215], v[94:97]
	v_mfma_f32_16x16x32_bf16 v[90:93], v[158:161], v[212:215], v[90:93]
	v_mfma_f32_16x16x32_bf16 v[78:81], v[134:137], v[220:223], v[78:81]
	v_mfma_f32_16x16x32_bf16 v[74:77], v[158:161], v[220:223], v[74:77]
	v_mfma_f32_16x16x32_bf16 v[118:121], v[172:175], v[188:191], v[118:121]
	v_mfma_f32_16x16x32_bf16 v[114:117], v[180:183], v[188:191], v[114:117]
	v_mfma_f32_16x16x32_bf16 v[102:105], v[172:175], v[196:199], v[102:105]
	v_mfma_f32_16x16x32_bf16 v[98:101], v[180:183], v[196:199], v[98:101]
	v_mfma_f32_16x16x32_bf16 v[86:89], v[172:175], v[208:211], v[86:89]
	v_mfma_f32_16x16x32_bf16 v[82:85], v[180:183], v[208:211], v[82:85]
	v_mfma_f32_16x16x32_bf16 v[70:73], v[172:175], v[216:219], v[70:73]
	v_mfma_f32_16x16x32_bf16 v[66:69], v[180:183], v[216:219], v[66:69]
	v_mfma_f32_16x16x32_bf16 v[118:121], v[176:179], v[192:195], v[118:121]
	v_mfma_f32_16x16x32_bf16 v[114:117], v[184:187], v[192:195], v[114:117]
	v_mfma_f32_16x16x32_bf16 v[102:105], v[176:179], v[204:207], v[102:105]
	v_mfma_f32_16x16x32_bf16 v[98:101], v[184:187], v[204:207], v[98:101]
	v_mfma_f32_16x16x32_bf16 v[86:89], v[176:179], v[212:215], v[86:89]
	v_mfma_f32_16x16x32_bf16 v[82:85], v[184:187], v[212:215], v[82:85]
	v_mfma_f32_16x16x32_bf16 v[70:73], v[176:179], v[220:223], v[70:73]
	v_mfma_f32_16x16x32_bf16 v[66:69], v[184:187], v[220:223], v[66:69]
	s_setprio 0
	s_barrier
	s_add_i32 s52, s45, s13
	v_lshl_add_u64 v[200:201], s[30:31], 0, v[138:139]
	s_mov_b32 m0, s52
	ds_read_b128 v[188:191], v171 offset:16384
	ds_read_b128 v[192:195], v171 offset:17408
	ds_read_b128 v[196:199], v171 offset:18432
	ds_read_b128 v[204:207], v171 offset:19456
	ds_read_b128 v[208:211], v171 offset:20480
	ds_read_b128 v[212:215], v171 offset:21504
	ds_read_b128 v[216:219], v171 offset:22528
	ds_read_b128 v[220:223], v171 offset:23552
	global_load_lds_dwordx4 v[200:201], off
	s_add_i32 m0, s52, 0x2000
	s_add_u32 s52, s30, 0x80000
	v_lshl_add_u64 v[224:225], s[30:31], 0, v[140:141]
	s_addc_u32 s53, s31, 0
	s_add_i32 s54, s46, s13
	global_load_lds_dwordx4 v[224:225], off
	v_lshl_add_u64 v[226:227], s[52:53], 0, v[138:139]
	s_mov_b32 m0, s54
	v_lshl_add_u64 v[228:229], s[34:35], 0, v[140:141]
	global_load_lds_dwordx4 v[226:227], off
	v_lshl_add_u64 v[226:227], s[52:53], 0, v[140:141]
	s_add_i32 m0, s54, 0x2000
	s_nop 0
	global_load_lds_dwordx4 v[226:227], off
	v_lshl_add_u64 v[226:227], s[34:35], 0, v[138:139]
	s_mov_b32 m0, s36
	s_nop 0
	global_load_lds_dwordx4 v[226:227], off
	s_mov_b32 m0, s37
	s_nop 0
	global_load_lds_dwordx4 v[228:229], off
	s_waitcnt vmcnt(8)
	s_waitcnt lgkmcnt(0)
	s_barrier
	s_setprio 1
	s_waitcnt lgkmcnt(0)
	v_mfma_f32_16x16x32_bf16 v[62:65], v[130:133], v[188:191], v[62:65]
	v_mfma_f32_16x16x32_bf16 v[58:61], v[154:157], v[188:191], v[58:61]
	v_mfma_f32_16x16x32_bf16 v[46:49], v[130:133], v[196:199], v[46:49]
	v_mfma_f32_16x16x32_bf16 v[42:45], v[154:157], v[196:199], v[42:45]
	v_mfma_f32_16x16x32_bf16 v[30:33], v[130:133], v[208:211], v[30:33]
	v_mfma_f32_16x16x32_bf16 v[26:29], v[154:157], v[208:211], v[26:29]
	v_mfma_f32_16x16x32_bf16 v[14:17], v[130:133], v[216:219], v[14:17]
	v_mfma_f32_16x16x32_bf16 v[10:13], v[154:157], v[216:219], v[10:13]
	v_mfma_f32_16x16x32_bf16 v[62:65], v[134:137], v[192:195], v[62:65]
	v_mfma_f32_16x16x32_bf16 v[58:61], v[158:161], v[192:195], v[58:61]
	v_mfma_f32_16x16x32_bf16 v[46:49], v[134:137], v[204:207], v[46:49]
	v_mfma_f32_16x16x32_bf16 v[42:45], v[158:161], v[204:207], v[42:45]
	v_mfma_f32_16x16x32_bf16 v[30:33], v[134:137], v[212:215], v[30:33]
	v_mfma_f32_16x16x32_bf16 v[26:29], v[158:161], v[212:215], v[26:29]
	v_mfma_f32_16x16x32_bf16 v[14:17], v[134:137], v[220:223], v[14:17]
	v_mfma_f32_16x16x32_bf16 v[10:13], v[158:161], v[220:223], v[10:13]
	v_mfma_f32_16x16x32_bf16 v[54:57], v[172:175], v[188:191], v[54:57]
	v_mfma_f32_16x16x32_bf16 v[50:53], v[180:183], v[188:191], v[50:53]
	v_mfma_f32_16x16x32_bf16 v[38:41], v[172:175], v[196:199], v[38:41]
	v_mfma_f32_16x16x32_bf16 v[34:37], v[180:183], v[196:199], v[34:37]
	v_mfma_f32_16x16x32_bf16 v[22:25], v[172:175], v[208:211], v[22:25]
	v_mfma_f32_16x16x32_bf16 v[18:21], v[180:183], v[208:211], v[18:21]
	v_mfma_f32_16x16x32_bf16 v[6:9], v[172:175], v[216:219], v[6:9]
	v_mfma_f32_16x16x32_bf16 v[2:5], v[180:183], v[216:219], v[2:5]
	v_mfma_f32_16x16x32_bf16 v[54:57], v[176:179], v[192:195], v[54:57]
	v_mfma_f32_16x16x32_bf16 v[50:53], v[184:187], v[192:195], v[50:53]
	v_mfma_f32_16x16x32_bf16 v[38:41], v[176:179], v[204:207], v[38:41]
	v_mfma_f32_16x16x32_bf16 v[34:37], v[184:187], v[204:207], v[34:37]
	v_mfma_f32_16x16x32_bf16 v[22:25], v[176:179], v[212:215], v[22:25]
	v_mfma_f32_16x16x32_bf16 v[18:21], v[184:187], v[212:215], v[18:21]
	v_mfma_f32_16x16x32_bf16 v[6:9], v[176:179], v[220:223], v[6:9]
	v_mfma_f32_16x16x32_bf16 v[2:5], v[184:187], v[220:223], v[2:5]
	s_setprio 0
	s_barrier
	s_add_i32 s52, 0, 0x18000
	s_add_i32 s53, 0, 0x1c000
	v_add_u32_e32 v158, s52, v163
	v_add_u32_e32 v184, s53, v163
	ds_read_b128 v[130:133], v158
	ds_read_b128 v[134:137], v158 offset:1024
	ds_read_b128 v[154:157], v158 offset:2048
	ds_read_b128 v[158:161], v158 offset:3072
	ds_read_b128 v[172:175], v184
	ds_read_b128 v[176:179], v184 offset:1024
	ds_read_b128 v[180:183], v184 offset:2048
	ds_read_b128 v[184:187], v184 offset:3072
	s_add_u32 s34, s34, 0x80000
	s_addc_u32 s35, s35, 0
	s_mov_b32 m0, s38
	v_lshl_add_u64 v[230:231], s[34:35], 0, v[138:139]
	ds_read_b128 v[188:191], v171 offset:32768
	ds_read_b128 v[192:195], v171 offset:33792
	ds_read_b128 v[196:199], v171 offset:34816
	ds_read_b128 v[204:207], v171 offset:35840
	ds_read_b128 v[208:211], v171 offset:36864
	ds_read_b128 v[212:215], v171 offset:37888
	ds_read_b128 v[216:219], v171 offset:38912
	ds_read_b128 v[220:223], v171 offset:39936
	global_load_lds_dwordx4 v[230:231], off
	v_lshl_add_u64 v[230:231], s[34:35], 0, v[140:141]
	s_mov_b32 m0, s39
	s_nop 0
	global_load_lds_dwordx4 v[230:231], off
	s_waitcnt vmcnt(8)
	s_waitcnt lgkmcnt(0)
	s_barrier
	s_setprio 1
	s_waitcnt lgkmcnt(0)
	v_mfma_f32_16x16x32_bf16 v[126:129], v[130:133], v[188:191], v[126:129]
	v_mfma_f32_16x16x32_bf16 v[122:125], v[154:157], v[188:191], v[122:125]
	v_mfma_f32_16x16x32_bf16 v[110:113], v[130:133], v[196:199], v[110:113]
	v_mfma_f32_16x16x32_bf16 v[106:109], v[154:157], v[196:199], v[106:109]
	v_mfma_f32_16x16x32_bf16 v[94:97], v[130:133], v[208:211], v[94:97]
	v_mfma_f32_16x16x32_bf16 v[90:93], v[154:157], v[208:211], v[90:93]
	v_mfma_f32_16x16x32_bf16 v[78:81], v[130:133], v[216:219], v[78:81]
	v_mfma_f32_16x16x32_bf16 v[74:77], v[154:157], v[216:219], v[74:77]
	v_mfma_f32_16x16x32_bf16 v[126:129], v[134:137], v[192:195], v[126:129]
	v_mfma_f32_16x16x32_bf16 v[122:125], v[158:161], v[192:195], v[122:125]
	v_mfma_f32_16x16x32_bf16 v[110:113], v[134:137], v[204:207], v[110:113]
	v_mfma_f32_16x16x32_bf16 v[106:109], v[158:161], v[204:207], v[106:109]
	v_mfma_f32_16x16x32_bf16 v[94:97], v[134:137], v[212:215], v[94:97]
	v_mfma_f32_16x16x32_bf16 v[90:93], v[158:161], v[212:215], v[90:93]
	v_mfma_f32_16x16x32_bf16 v[78:81], v[134:137], v[220:223], v[78:81]
	v_mfma_f32_16x16x32_bf16 v[74:77], v[158:161], v[220:223], v[74:77]
	v_mfma_f32_16x16x32_bf16 v[118:121], v[172:175], v[188:191], v[118:121]
	v_mfma_f32_16x16x32_bf16 v[114:117], v[180:183], v[188:191], v[114:117]
	v_mfma_f32_16x16x32_bf16 v[102:105], v[172:175], v[196:199], v[102:105]
	v_mfma_f32_16x16x32_bf16 v[98:101], v[180:183], v[196:199], v[98:101]
	v_mfma_f32_16x16x32_bf16 v[86:89], v[172:175], v[208:211], v[86:89]
	v_mfma_f32_16x16x32_bf16 v[82:85], v[180:183], v[208:211], v[82:85]
	v_mfma_f32_16x16x32_bf16 v[70:73], v[172:175], v[216:219], v[70:73]
	v_mfma_f32_16x16x32_bf16 v[66:69], v[180:183], v[216:219], v[66:69]
	v_mfma_f32_16x16x32_bf16 v[118:121], v[176:179], v[192:195], v[118:121]
	v_mfma_f32_16x16x32_bf16 v[114:117], v[184:187], v[192:195], v[114:117]
	v_mfma_f32_16x16x32_bf16 v[102:105], v[176:179], v[204:207], v[102:105]
	v_mfma_f32_16x16x32_bf16 v[98:101], v[184:187], v[204:207], v[98:101]
	v_mfma_f32_16x16x32_bf16 v[86:89], v[176:179], v[212:215], v[86:89]
	v_mfma_f32_16x16x32_bf16 v[82:85], v[184:187], v[212:215], v[82:85]
	v_mfma_f32_16x16x32_bf16 v[70:73], v[176:179], v[220:223], v[70:73]
	v_mfma_f32_16x16x32_bf16 v[66:69], v[184:187], v[220:223], v[66:69]
	s_setprio 0
	s_barrier
	s_add_i32 s34, s52, s13
	v_lshl_add_u64 v[200:201], v[200:201], 0, s[6:7]
	s_mov_b32 m0, s34
	ds_read_b128 v[188:191], v171 offset:49152
	ds_read_b128 v[192:195], v171 offset:50176
	ds_read_b128 v[196:199], v171 offset:51200
	ds_read_b128 v[204:207], v171 offset:52224
	ds_read_b128 v[208:211], v171 offset:53248
	ds_read_b128 v[212:215], v171 offset:54272
	ds_read_b128 v[216:219], v171 offset:55296
	ds_read_b128 v[220:223], v171 offset:56320
	global_load_lds_dwordx4 v[200:201], off
	s_add_i32 m0, s34, 0x2000
	s_add_u32 s30, s30, 0x80080
	v_lshl_add_u64 v[200:201], v[224:225], 0, s[6:7]
	s_addc_u32 s31, s31, 0
	s_add_i32 s34, s53, s13
	global_load_lds_dwordx4 v[200:201], off
	v_lshl_add_u64 v[200:201], s[30:31], 0, v[138:139]
	s_mov_b32 m0, s34
	s_nop 0
	global_load_lds_dwordx4 v[200:201], off
	v_lshl_add_u64 v[200:201], s[30:31], 0, v[140:141]
	s_add_i32 m0, s34, 0x2000
	s_nop 0
	global_load_lds_dwordx4 v[200:201], off
	v_lshl_add_u64 v[200:201], v[226:227], 0, s[6:7]
	s_mov_b32 m0, s40
	s_nop 0
	global_load_lds_dwordx4 v[200:201], off
	v_lshl_add_u64 v[200:201], v[228:229], 0, s[6:7]
	s_mov_b32 m0, s41
	s_nop 0
	global_load_lds_dwordx4 v[200:201], off
	s_waitcnt vmcnt(8)
	s_waitcnt lgkmcnt(0)
	s_barrier
	s_setprio 1
	s_waitcnt lgkmcnt(0)
	v_mfma_f32_16x16x32_bf16 v[62:65], v[130:133], v[188:191], v[62:65]
	v_mfma_f32_16x16x32_bf16 v[58:61], v[154:157], v[188:191], v[58:61]
	v_mfma_f32_16x16x32_bf16 v[46:49], v[130:133], v[196:199], v[46:49]
	v_mfma_f32_16x16x32_bf16 v[42:45], v[154:157], v[196:199], v[42:45]
	v_mfma_f32_16x16x32_bf16 v[30:33], v[130:133], v[208:211], v[30:33]
	v_mfma_f32_16x16x32_bf16 v[26:29], v[154:157], v[208:211], v[26:29]
	v_mfma_f32_16x16x32_bf16 v[14:17], v[130:133], v[216:219], v[14:17]
	v_mfma_f32_16x16x32_bf16 v[10:13], v[154:157], v[216:219], v[10:13]
	v_mfma_f32_16x16x32_bf16 v[62:65], v[134:137], v[192:195], v[62:65]
	v_mfma_f32_16x16x32_bf16 v[58:61], v[158:161], v[192:195], v[58:61]
	v_mfma_f32_16x16x32_bf16 v[46:49], v[134:137], v[204:207], v[46:49]
	v_mfma_f32_16x16x32_bf16 v[42:45], v[158:161], v[204:207], v[42:45]
	v_mfma_f32_16x16x32_bf16 v[30:33], v[134:137], v[212:215], v[30:33]
	v_mfma_f32_16x16x32_bf16 v[26:29], v[158:161], v[212:215], v[26:29]
	v_mfma_f32_16x16x32_bf16 v[14:17], v[134:137], v[220:223], v[14:17]
	v_mfma_f32_16x16x32_bf16 v[10:13], v[158:161], v[220:223], v[10:13]
	v_mfma_f32_16x16x32_bf16 v[54:57], v[172:175], v[188:191], v[54:57]
	v_mfma_f32_16x16x32_bf16 v[50:53], v[180:183], v[188:191], v[50:53]
	v_mfma_f32_16x16x32_bf16 v[38:41], v[172:175], v[196:199], v[38:41]
	v_mfma_f32_16x16x32_bf16 v[34:37], v[180:183], v[196:199], v[34:37]
	v_mfma_f32_16x16x32_bf16 v[22:25], v[172:175], v[208:211], v[22:25]
	v_mfma_f32_16x16x32_bf16 v[18:21], v[180:183], v[208:211], v[18:21]
	v_mfma_f32_16x16x32_bf16 v[6:9], v[172:175], v[216:219], v[6:9]
	v_mfma_f32_16x16x32_bf16 v[2:5], v[180:183], v[216:219], v[2:5]
	v_mfma_f32_16x16x32_bf16 v[54:57], v[176:179], v[192:195], v[54:57]
	v_mfma_f32_16x16x32_bf16 v[50:53], v[184:187], v[192:195], v[50:53]
	v_mfma_f32_16x16x32_bf16 v[38:41], v[176:179], v[204:207], v[38:41]
	v_mfma_f32_16x16x32_bf16 v[34:37], v[184:187], v[204:207], v[34:37]
	v_mfma_f32_16x16x32_bf16 v[22:25], v[176:179], v[212:215], v[22:25]
	v_mfma_f32_16x16x32_bf16 v[18:21], v[184:187], v[212:215], v[18:21]
	v_mfma_f32_16x16x32_bf16 v[6:9], v[176:179], v[220:223], v[6:9]
	v_mfma_f32_16x16x32_bf16 v[2:5], v[184:187], v[220:223], v[2:5]
	s_setprio 0
	s_barrier
	s_add_i32 s51, s51, 2
	s_add_u32 s28, s28, 0x100
	s_addc_u32 s29, s29, 0
	s_add_u32 s49, s49, 0x100
	s_addc_u32 s50, s50, 0
	s_cmp_gt_u32 s51, 29
	s_cbranch_scc0 .LBB0_1966
	s_and_b64 vcc, exec, s[8:9]
	s_cbranch_vccz .LBB0_1969
	s_barrier

.LBB0_2068:
	ds_read_b128 v[106:109], v199
	ds_read_b128 v[114:117], v199 offset:1024
	ds_read_b128 v[118:121], v199 offset:2048
	ds_read_b128 v[122:125], v199 offset:3072
	ds_read_b128 v[126:129], v200
	ds_read_b128 v[134:137], v200 offset:1024
	ds_read_b128 v[138:141], v200 offset:2048
	ds_read_b128 v[142:145], v200 offset:3072
	s_add_u32 s26, s24, 0xfff80080
	s_addc_u32 s27, s25, -1
	s_cmp_eq_u32 s49, 28
	s_cselect_b32 s29, s15, s27
	s_cselect_b32 s28, s21, s26
	s_cselect_b32 s27, s13, s48
	s_cselect_b32 s26, s23, s47
	v_lshl_add_u64 v[224:225], s[24:25], 0, v[186:187]
	s_add_i32 m0, s31, 0xc000
	ds_read_b128 v[146:149], v201
	ds_read_b128 v[166:169], v201 offset:1024
	ds_read_b128 v[170:173], v201 offset:2048
	ds_read_b128 v[204:207], v201 offset:3072
	ds_read_b128 v[208:211], v201 offset:4096
	ds_read_b128 v[212:215], v201 offset:5120
	ds_read_b128 v[216:219], v201 offset:6144
	ds_read_b128 v[220:223], v201 offset:7168
	global_load_lds_dwordx4 v[224:225], off
	v_lshl_add_u64 v[224:225], s[24:25], 0, v[188:189]
	s_add_i32 m0, s31, 0xe000
	s_nop 0
	global_load_lds_dwordx4 v[224:225], off
	s_waitcnt vmcnt(8)
	s_waitcnt lgkmcnt(0)
	s_barrier
	s_setprio 1
	s_waitcnt lgkmcnt(0)
	v_mfma_f32_16x16x32_bf16 v[162:165], v[106:109], v[146:149], v[162:165]
	v_mfma_f32_16x16x32_bf16 v[158:161], v[118:121], v[146:149], v[158:161]
	v_mfma_f32_16x16x32_bf16 v[130:133], v[106:109], v[170:173], v[130:133]
	v_mfma_f32_16x16x32_bf16 v[110:113], v[118:121], v[170:173], v[110:113]
	v_mfma_f32_16x16x32_bf16 v[94:97], v[106:109], v[208:211], v[94:97]
	v_mfma_f32_16x16x32_bf16 v[90:93], v[118:121], v[208:211], v[90:93]
	v_mfma_f32_16x16x32_bf16 v[78:81], v[106:109], v[216:219], v[78:81]
	v_mfma_f32_16x16x32_bf16 v[74:77], v[118:121], v[216:219], v[74:77]
	v_mfma_f32_16x16x32_bf16 v[162:165], v[114:117], v[166:169], v[162:165]
	v_mfma_f32_16x16x32_bf16 v[158:161], v[122:125], v[166:169], v[158:161]
	v_mfma_f32_16x16x32_bf16 v[130:133], v[114:117], v[204:207], v[130:133]
	v_mfma_f32_16x16x32_bf16 v[110:113], v[122:125], v[204:207], v[110:113]
	v_mfma_f32_16x16x32_bf16 v[94:97], v[114:117], v[212:215], v[94:97]
	v_mfma_f32_16x16x32_bf16 v[90:93], v[122:125], v[212:215], v[90:93]
	v_mfma_f32_16x16x32_bf16 v[78:81], v[114:117], v[220:223], v[78:81]
	v_mfma_f32_16x16x32_bf16 v[74:77], v[122:125], v[220:223], v[74:77]
	v_mfma_f32_16x16x32_bf16 v[154:157], v[126:129], v[146:149], v[154:157]
	v_mfma_f32_16x16x32_bf16 v[102:105], v[126:129], v[170:173], v[102:105]
	v_mfma_f32_16x16x32_bf16 v[98:101], v[138:141], v[170:173], v[98:101]
	v_mfma_f32_16x16x32_bf16 v[86:89], v[126:129], v[208:211], v[86:89]
	v_mfma_f32_16x16x32_bf16 v[82:85], v[138:141], v[208:211], v[82:85]
	v_mfma_f32_16x16x32_bf16 v[70:73], v[126:129], v[216:219], v[70:73]
	v_mfma_f32_16x16x32_bf16 v[66:69], v[138:141], v[216:219], v[66:69]
	v_mfma_f32_16x16x32_bf16 v[154:157], v[134:137], v[166:169], v[154:157]
	v_mfma_f32_16x16x32_bf16 v[146:149], v[138:141], v[146:149], v[150:153]
	v_mfma_f32_16x16x32_bf16 v[102:105], v[134:137], v[204:207], v[102:105]
	v_mfma_f32_16x16x32_bf16 v[98:101], v[142:145], v[204:207], v[98:101]
	v_mfma_f32_16x16x32_bf16 v[86:89], v[134:137], v[212:215], v[86:89]
	v_mfma_f32_16x16x32_bf16 v[82:85], v[142:145], v[212:215], v[82:85]
	v_mfma_f32_16x16x32_bf16 v[70:73], v[134:137], v[220:223], v[70:73]
	v_mfma_f32_16x16x32_bf16 v[66:69], v[142:145], v[220:223], v[66:69]
	v_mfma_f32_16x16x32_bf16 v[146:149], v[142:145], v[166:169], v[146:149]
	s_setprio 0
	s_barrier
	s_add_i32 s50, s42, s30
	v_lshl_add_u64 v[224:225], s[26:27], 0, v[176:177]
	s_mov_b32 m0, s50
	ds_read_b128 v[150:153], v201 offset:16384
	ds_read_b128 v[166:169], v201 offset:17408
	ds_read_b128 v[170:173], v201 offset:18432
	ds_read_b128 v[204:207], v201 offset:19456
	ds_read_b128 v[208:211], v201 offset:20480
	ds_read_b128 v[212:215], v201 offset:21504
	ds_read_b128 v[216:219], v201 offset:22528
	ds_read_b128 v[220:223], v201 offset:23552
	global_load_lds_dwordx4 v[224:225], off
	s_add_i32 m0, s50, 0x2000
	s_add_u32 s50, s26, 0x80000
	v_lshl_add_u64 v[226:227], s[26:27], 0, v[180:181]
	s_addc_u32 s51, s27, 0
	s_add_i32 s52, s43, s30
	global_load_lds_dwordx4 v[226:227], off
	v_lshl_add_u64 v[228:229], s[50:51], 0, v[176:177]
	s_mov_b32 m0, s52
	v_lshl_add_u64 v[230:231], s[28:29], 0, v[178:179]
	global_load_lds_dwordx4 v[228:229], off
	v_lshl_add_u64 v[228:229], s[50:51], 0, v[180:181]
	s_add_i32 m0, s52, 0x2000
	s_nop 0
	global_load_lds_dwordx4 v[228:229], off
	v_lshl_add_u64 v[228:229], s[28:29], 0, v[174:175]
	s_mov_b32 m0, s31
	s_nop 0
	global_load_lds_dwordx4 v[228:229], off
	s_mov_b32 m0, s34
	s_nop 0
	global_load_lds_dwordx4 v[230:231], off
	s_waitcnt vmcnt(8)
	s_waitcnt lgkmcnt(0)
	s_barrier
	s_setprio 1
	s_waitcnt lgkmcnt(0)
	v_mfma_f32_16x16x32_bf16 v[62:65], v[106:109], v[150:153], v[62:65]
	v_mfma_f32_16x16x32_bf16 v[58:61], v[118:121], v[150:153], v[58:61]
	v_mfma_f32_16x16x32_bf16 v[46:49], v[106:109], v[170:173], v[46:49]
	v_mfma_f32_16x16x32_bf16 v[42:45], v[118:121], v[170:173], v[42:45]
	v_mfma_f32_16x16x32_bf16 v[30:33], v[106:109], v[208:211], v[30:33]
	v_mfma_f32_16x16x32_bf16 v[26:29], v[118:121], v[208:211], v[26:29]
	v_mfma_f32_16x16x32_bf16 v[14:17], v[106:109], v[216:219], v[14:17]
	v_mfma_f32_16x16x32_bf16 v[10:13], v[118:121], v[216:219], v[10:13]
	v_mfma_f32_16x16x32_bf16 v[62:65], v[114:117], v[166:169], v[62:65]
	v_mfma_f32_16x16x32_bf16 v[58:61], v[122:125], v[166:169], v[58:61]
	v_mfma_f32_16x16x32_bf16 v[46:49], v[114:117], v[204:207], v[46:49]
	v_mfma_f32_16x16x32_bf16 v[42:45], v[122:125], v[204:207], v[42:45]
	v_mfma_f32_16x16x32_bf16 v[30:33], v[114:117], v[212:215], v[30:33]
	v_mfma_f32_16x16x32_bf16 v[26:29], v[122:125], v[212:215], v[26:29]
	v_mfma_f32_16x16x32_bf16 v[14:17], v[114:117], v[220:223], v[14:17]
	v_mfma_f32_16x16x32_bf16 v[10:13], v[122:125], v[220:223], v[10:13]
	v_mfma_f32_16x16x32_bf16 v[54:57], v[126:129], v[150:153], v[54:57]
	v_mfma_f32_16x16x32_bf16 v[50:53], v[138:141], v[150:153], v[50:53]
	v_mfma_f32_16x16x32_bf16 v[38:41], v[126:129], v[170:173], v[38:41]
	v_mfma_f32_16x16x32_bf16 v[34:37], v[138:141], v[170:173], v[34:37]
	v_mfma_f32_16x16x32_bf16 v[22:25], v[126:129], v[208:211], v[22:25]
	v_mfma_f32_16x16x32_bf16 v[18:21], v[138:141], v[208:211], v[18:21]
	v_mfma_f32_16x16x32_bf16 v[6:9], v[126:129], v[216:219], v[6:9]
	v_mfma_f32_16x16x32_bf16 v[2:5], v[138:141], v[216:219], v[2:5]
	v_mfma_f32_16x16x32_bf16 v[54:57], v[134:137], v[166:169], v[54:57]
	v_mfma_f32_16x16x32_bf16 v[50:53], v[142:145], v[166:169], v[50:53]
	v_mfma_f32_16x16x32_bf16 v[38:41], v[134:137], v[204:207], v[38:41]
	v_mfma_f32_16x16x32_bf16 v[34:37], v[142:145], v[204:207], v[34:37]
	v_mfma_f32_16x16x32_bf16 v[22:25], v[134:137], v[212:215], v[22:25]
	v_mfma_f32_16x16x32_bf16 v[18:21], v[142:145], v[212:215], v[18:21]
	v_mfma_f32_16x16x32_bf16 v[6:9], v[134:137], v[220:223], v[6:9]
	v_mfma_f32_16x16x32_bf16 v[2:5], v[142:145], v[220:223], v[2:5]
	s_setprio 0
	s_barrier
	s_add_i32 s50, 0, 0x18000
	s_add_i32 s51, 0, 0x1c000
	v_add_u32_e32 v122, s50, v195
	v_add_u32_e32 v142, s51, v195
	ds_read_b128 v[106:109], v122
	ds_read_b128 v[114:117], v122 offset:1024
	ds_read_b128 v[118:121], v122 offset:2048
	ds_read_b128 v[122:125], v122 offset:3072
	ds_read_b128 v[126:129], v142
	ds_read_b128 v[134:137], v142 offset:1024
	ds_read_b128 v[138:141], v142 offset:2048
	ds_read_b128 v[142:145], v142 offset:3072
	s_add_u32 s28, s28, 0x80000
	s_addc_u32 s29, s29, 0
	s_mov_b32 m0, s35
	v_lshl_add_u64 v[232:233], s[28:29], 0, v[174:175]
	ds_read_b128 v[150:153], v201 offset:32768
	ds_read_b128 v[166:169], v201 offset:33792
	ds_read_b128 v[170:173], v201 offset:34816
	ds_read_b128 v[204:207], v201 offset:35840
	ds_read_b128 v[208:211], v201 offset:36864
	ds_read_b128 v[212:215], v201 offset:37888
	ds_read_b128 v[216:219], v201 offset:38912
	ds_read_b128 v[220:223], v201 offset:39936
	global_load_lds_dwordx4 v[232:233], off
	v_lshl_add_u64 v[232:233], s[28:29], 0, v[178:179]
	s_mov_b32 m0, s37
	s_nop 0
	global_load_lds_dwordx4 v[232:233], off
	s_waitcnt vmcnt(8)
	s_waitcnt lgkmcnt(0)
	s_barrier
	s_setprio 1
	s_waitcnt lgkmcnt(0)
	v_mfma_f32_16x16x32_bf16 v[162:165], v[106:109], v[150:153], v[162:165]
	v_mfma_f32_16x16x32_bf16 v[158:161], v[118:121], v[150:153], v[158:161]
	v_mfma_f32_16x16x32_bf16 v[130:133], v[106:109], v[170:173], v[130:133]
	v_mfma_f32_16x16x32_bf16 v[110:113], v[118:121], v[170:173], v[110:113]
	v_mfma_f32_16x16x32_bf16 v[94:97], v[106:109], v[208:211], v[94:97]
	v_mfma_f32_16x16x32_bf16 v[90:93], v[118:121], v[208:211], v[90:93]
	v_mfma_f32_16x16x32_bf16 v[78:81], v[106:109], v[216:219], v[78:81]
	v_mfma_f32_16x16x32_bf16 v[74:77], v[118:121], v[216:219], v[74:77]
	v_mfma_f32_16x16x32_bf16 v[162:165], v[114:117], v[166:169], v[162:165]
	v_mfma_f32_16x16x32_bf16 v[158:161], v[122:125], v[166:169], v[158:161]
	v_mfma_f32_16x16x32_bf16 v[130:133], v[114:117], v[204:207], v[130:133]
	v_mfma_f32_16x16x32_bf16 v[110:113], v[122:125], v[204:207], v[110:113]
	v_mfma_f32_16x16x32_bf16 v[94:97], v[114:117], v[212:215], v[94:97]
	v_mfma_f32_16x16x32_bf16 v[90:93], v[122:125], v[212:215], v[90:93]
	v_mfma_f32_16x16x32_bf16 v[78:81], v[114:117], v[220:223], v[78:81]
	v_mfma_f32_16x16x32_bf16 v[74:77], v[122:125], v[220:223], v[74:77]
	v_mfma_f32_16x16x32_bf16 v[154:157], v[126:129], v[150:153], v[154:157]
	v_mfma_f32_16x16x32_bf16 v[146:149], v[138:141], v[150:153], v[146:149]
	v_mfma_f32_16x16x32_bf16 v[102:105], v[126:129], v[170:173], v[102:105]
	v_mfma_f32_16x16x32_bf16 v[98:101], v[138:141], v[170:173], v[98:101]
	v_mfma_f32_16x16x32_bf16 v[86:89], v[126:129], v[208:211], v[86:89]
	v_mfma_f32_16x16x32_bf16 v[82:85], v[138:141], v[208:211], v[82:85]
	v_mfma_f32_16x16x32_bf16 v[70:73], v[126:129], v[216:219], v[70:73]
	v_mfma_f32_16x16x32_bf16 v[66:69], v[138:141], v[216:219], v[66:69]
	v_mfma_f32_16x16x32_bf16 v[154:157], v[134:137], v[166:169], v[154:157]
	v_mfma_f32_16x16x32_bf16 v[150:153], v[142:145], v[166:169], v[146:149]
	v_mfma_f32_16x16x32_bf16 v[102:105], v[134:137], v[204:207], v[102:105]
	v_mfma_f32_16x16x32_bf16 v[98:101], v[142:145], v[204:207], v[98:101]
	v_mfma_f32_16x16x32_bf16 v[86:89], v[134:137], v[212:215], v[86:89]
	v_mfma_f32_16x16x32_bf16 v[82:85], v[142:145], v[212:215], v[82:85]
	v_mfma_f32_16x16x32_bf16 v[70:73], v[134:137], v[220:223], v[70:73]
	v_mfma_f32_16x16x32_bf16 v[66:69], v[142:145], v[220:223], v[66:69]
	s_setprio 0
	s_barrier
	s_add_i32 s28, s50, s30
	v_lshl_add_u64 v[224:225], v[224:225], 0, s[6:7]
	s_mov_b32 m0, s28
	ds_read_b128 v[146:149], v201 offset:49152
	ds_read_b128 v[166:169], v201 offset:50176
	ds_read_b128 v[170:173], v201 offset:51200
	ds_read_b128 v[204:207], v201 offset:52224
	ds_read_b128 v[208:211], v201 offset:53248
	ds_read_b128 v[212:215], v201 offset:54272
	ds_read_b128 v[216:219], v201 offset:55296
	ds_read_b128 v[220:223], v201 offset:56320
	global_load_lds_dwordx4 v[224:225], off
	s_add_i32 m0, s28, 0x2000
	s_add_u32 s26, s26, 0x80080
	v_lshl_add_u64 v[224:225], v[226:227], 0, s[6:7]
	s_addc_u32 s27, s27, 0
	s_add_i32 s28, s51, s30
	global_load_lds_dwordx4 v[224:225], off
	v_lshl_add_u64 v[224:225], s[26:27], 0, v[176:177]
	s_mov_b32 m0, s28
	s_nop 0
	global_load_lds_dwordx4 v[224:225], off
	v_lshl_add_u64 v[224:225], s[26:27], 0, v[180:181]
	s_add_i32 m0, s28, 0x2000
	s_nop 0
	global_load_lds_dwordx4 v[224:225], off
	v_lshl_add_u64 v[224:225], v[228:229], 0, s[6:7]
	s_mov_b32 m0, s38
	s_nop 0
	global_load_lds_dwordx4 v[224:225], off
	v_lshl_add_u64 v[224:225], v[230:231], 0, s[6:7]
	s_mov_b32 m0, s39
	s_nop 0
	global_load_lds_dwordx4 v[224:225], off
	s_waitcnt vmcnt(8)
	s_waitcnt lgkmcnt(0)
	s_barrier
	s_setprio 1
	s_waitcnt lgkmcnt(0)
	v_mfma_f32_16x16x32_bf16 v[62:65], v[106:109], v[146:149], v[62:65]
	v_mfma_f32_16x16x32_bf16 v[58:61], v[118:121], v[146:149], v[58:61]
	v_mfma_f32_16x16x32_bf16 v[46:49], v[106:109], v[170:173], v[46:49]
	v_mfma_f32_16x16x32_bf16 v[42:45], v[118:121], v[170:173], v[42:45]
	v_mfma_f32_16x16x32_bf16 v[30:33], v[106:109], v[208:211], v[30:33]
	v_mfma_f32_16x16x32_bf16 v[26:29], v[118:121], v[208:211], v[26:29]
	v_mfma_f32_16x16x32_bf16 v[14:17], v[106:109], v[216:219], v[14:17]
	v_mfma_f32_16x16x32_bf16 v[10:13], v[118:121], v[216:219], v[10:13]
	v_mfma_f32_16x16x32_bf16 v[62:65], v[114:117], v[166:169], v[62:65]
	v_mfma_f32_16x16x32_bf16 v[58:61], v[122:125], v[166:169], v[58:61]
	v_mfma_f32_16x16x32_bf16 v[46:49], v[114:117], v[204:207], v[46:49]
	v_mfma_f32_16x16x32_bf16 v[42:45], v[122:125], v[204:207], v[42:45]
	v_mfma_f32_16x16x32_bf16 v[30:33], v[114:117], v[212:215], v[30:33]
	v_mfma_f32_16x16x32_bf16 v[26:29], v[122:125], v[212:215], v[26:29]
	v_mfma_f32_16x16x32_bf16 v[14:17], v[114:117], v[220:223], v[14:17]
	v_mfma_f32_16x16x32_bf16 v[10:13], v[122:125], v[220:223], v[10:13]
	v_mfma_f32_16x16x32_bf16 v[54:57], v[126:129], v[146:149], v[54:57]
	v_mfma_f32_16x16x32_bf16 v[50:53], v[138:141], v[146:149], v[50:53]
	v_mfma_f32_16x16x32_bf16 v[38:41], v[126:129], v[170:173], v[38:41]
	v_mfma_f32_16x16x32_bf16 v[34:37], v[138:141], v[170:173], v[34:37]
	v_mfma_f32_16x16x32_bf16 v[22:25], v[126:129], v[208:211], v[22:25]
	v_mfma_f32_16x16x32_bf16 v[18:21], v[138:141], v[208:211], v[18:21]
	v_mfma_f32_16x16x32_bf16 v[6:9], v[126:129], v[216:219], v[6:9]
	v_mfma_f32_16x16x32_bf16 v[2:5], v[138:141], v[216:219], v[2:5]
	v_mfma_f32_16x16x32_bf16 v[54:57], v[134:137], v[166:169], v[54:57]
	v_mfma_f32_16x16x32_bf16 v[50:53], v[142:145], v[166:169], v[50:53]
	v_mfma_f32_16x16x32_bf16 v[38:41], v[134:137], v[204:207], v[38:41]
	v_mfma_f32_16x16x32_bf16 v[34:37], v[142:145], v[204:207], v[34:37]
	v_mfma_f32_16x16x32_bf16 v[22:25], v[134:137], v[212:215], v[22:25]
	v_mfma_f32_16x16x32_bf16 v[18:21], v[142:145], v[212:215], v[18:21]
	v_mfma_f32_16x16x32_bf16 v[6:9], v[134:137], v[220:223], v[6:9]
	v_mfma_f32_16x16x32_bf16 v[2:5], v[142:145], v[220:223], v[2:5]
	s_setprio 0
	s_barrier
	s_add_i32 s49, s49, 2
	s_add_u32 s24, s24, 0x100
	s_addc_u32 s25, s25, 0
	s_add_u32 s47, s47, 0x100
	s_addc_u32 s48, s48, 0
	s_cmp_gt_u32 s49, 29
	s_cbranch_scc0 .LBB0_2068
	s_and_b64 vcc, exec, s[8:9]
	s_cbranch_vccz .LBB0_2071
	s_barrier

.LBB0_2149:
	ds_read_b128 v[146:149], v163
	ds_read_b128 v[150:153], v163 offset:1024
	ds_read_b128 v[154:157], v163 offset:2048
	ds_read_b128 v[166:169], v163 offset:3072
	ds_read_b128 v[170:173], v164
	ds_read_b128 v[174:177], v164 offset:1024
	ds_read_b128 v[178:181], v164 offset:2048
	ds_read_b128 v[182:185], v164 offset:3072
	s_add_u32 s28, s26, 0x100
	s_addc_u32 s29, s27, 0
	s_cmpk_eq_i32 s50, 0x54
	s_cselect_b32 s35, s3, s29
	s_cselect_b32 s34, s2, s28
	s_cselect_b32 s31, s21, s25
	s_cselect_b32 s30, s20, s23
	v_lshl_add_u64 v[220:221], s[26:27], 0, v[138:139]
	s_add_i32 m0, s37, 0xc000
	ds_read_b128 v[186:189], v165
	ds_read_b128 v[190:193], v165 offset:1024
	ds_read_b128 v[194:197], v165 offset:2048
	ds_read_b128 v[198:201], v165 offset:3072
	ds_read_b128 v[204:207], v165 offset:4096
	ds_read_b128 v[208:211], v165 offset:5120
	ds_read_b128 v[212:215], v165 offset:6144
	ds_read_b128 v[216:219], v165 offset:7168
	global_load_lds_dwordx4 v[220:221], off
	v_lshl_add_u64 v[220:221], s[26:27], 0, v[140:141]
	s_add_i32 m0, s37, 0xe000
	s_nop 0
	global_load_lds_dwordx4 v[220:221], off
	s_waitcnt vmcnt(8)
	s_waitcnt lgkmcnt(0)
	s_barrier
	s_setprio 1
	s_waitcnt lgkmcnt(0)
	v_mfma_f32_16x16x32_bf16 v[126:129], v[146:149], v[186:189], v[126:129]
	v_mfma_f32_16x16x32_bf16 v[122:125], v[154:157], v[186:189], v[122:125]
	v_mfma_f32_16x16x32_bf16 v[110:113], v[146:149], v[194:197], v[110:113]
	v_mfma_f32_16x16x32_bf16 v[106:109], v[154:157], v[194:197], v[106:109]
	v_mfma_f32_16x16x32_bf16 v[94:97], v[146:149], v[204:207], v[94:97]
	v_mfma_f32_16x16x32_bf16 v[90:93], v[154:157], v[204:207], v[90:93]
	v_mfma_f32_16x16x32_bf16 v[78:81], v[146:149], v[212:215], v[78:81]
	v_mfma_f32_16x16x32_bf16 v[74:77], v[154:157], v[212:215], v[74:77]
	v_mfma_f32_16x16x32_bf16 v[126:129], v[150:153], v[190:193], v[126:129]
	v_mfma_f32_16x16x32_bf16 v[122:125], v[166:169], v[190:193], v[122:125]
	v_mfma_f32_16x16x32_bf16 v[110:113], v[150:153], v[198:201], v[110:113]
	v_mfma_f32_16x16x32_bf16 v[106:109], v[166:169], v[198:201], v[106:109]
	v_mfma_f32_16x16x32_bf16 v[94:97], v[150:153], v[208:211], v[94:97]
	v_mfma_f32_16x16x32_bf16 v[90:93], v[166:169], v[208:211], v[90:93]
	v_mfma_f32_16x16x32_bf16 v[78:81], v[150:153], v[216:219], v[78:81]
	v_mfma_f32_16x16x32_bf16 v[74:77], v[166:169], v[216:219], v[74:77]
	v_mfma_f32_16x16x32_bf16 v[118:121], v[170:173], v[186:189], v[118:121]
	v_mfma_f32_16x16x32_bf16 v[114:117], v[178:181], v[186:189], v[114:117]
	v_mfma_f32_16x16x32_bf16 v[102:105], v[170:173], v[194:197], v[102:105]
	v_mfma_f32_16x16x32_bf16 v[98:101], v[178:181], v[194:197], v[98:101]
	v_mfma_f32_16x16x32_bf16 v[86:89], v[170:173], v[204:207], v[86:89]
	v_mfma_f32_16x16x32_bf16 v[82:85], v[178:181], v[204:207], v[82:85]
	v_mfma_f32_16x16x32_bf16 v[70:73], v[170:173], v[212:215], v[70:73]
	v_mfma_f32_16x16x32_bf16 v[66:69], v[178:181], v[212:215], v[66:69]
	v_mfma_f32_16x16x32_bf16 v[118:121], v[174:177], v[190:193], v[118:121]
	v_mfma_f32_16x16x32_bf16 v[114:117], v[182:185], v[190:193], v[114:117]
	v_mfma_f32_16x16x32_bf16 v[102:105], v[174:177], v[198:201], v[102:105]
	v_mfma_f32_16x16x32_bf16 v[98:101], v[182:185], v[198:201], v[98:101]
	v_mfma_f32_16x16x32_bf16 v[86:89], v[174:177], v[208:211], v[86:89]
	v_mfma_f32_16x16x32_bf16 v[82:85], v[182:185], v[208:211], v[82:85]
	v_mfma_f32_16x16x32_bf16 v[70:73], v[174:177], v[216:219], v[70:73]
	v_mfma_f32_16x16x32_bf16 v[66:69], v[182:185], v[216:219], v[66:69]
	s_setprio 0
	s_barrier
	s_add_i32 s26, s44, s19
	v_lshl_add_u64 v[220:221], s[30:31], 0, v[130:131]
	s_mov_b32 m0, s26
	ds_read_b128 v[186:189], v165 offset:16384
	ds_read_b128 v[190:193], v165 offset:17408
	ds_read_b128 v[194:197], v165 offset:18432
	ds_read_b128 v[198:201], v165 offset:19456
	ds_read_b128 v[204:207], v165 offset:20480
	ds_read_b128 v[208:211], v165 offset:21504
	ds_read_b128 v[212:215], v165 offset:22528
	ds_read_b128 v[216:219], v165 offset:23552
	global_load_lds_dwordx4 v[220:221], off
	s_add_i32 m0, s26, 0x2000
	s_add_u32 s26, s30, 0x160000
	v_lshl_add_u64 v[222:223], s[30:31], 0, v[132:133]
	s_addc_u32 s27, s31, 0
	s_add_i32 s51, s45, s19
	global_load_lds_dwordx4 v[222:223], off
	v_lshl_add_u64 v[224:225], s[26:27], 0, v[130:131]
	s_mov_b32 m0, s51
	v_lshl_add_u64 v[226:227], s[34:35], 0, v[132:133]
	global_load_lds_dwordx4 v[224:225], off
	v_lshl_add_u64 v[224:225], s[26:27], 0, v[132:133]
	s_add_i32 m0, s51, 0x2000
	s_nop 0
	global_load_lds_dwordx4 v[224:225], off
	v_lshl_add_u64 v[224:225], s[34:35], 0, v[130:131]
	s_mov_b32 m0, s37
	s_nop 0
	global_load_lds_dwordx4 v[224:225], off
	s_mov_b32 m0, s38
	s_nop 0
	global_load_lds_dwordx4 v[226:227], off
	s_waitcnt vmcnt(8)
	s_waitcnt lgkmcnt(0)
	s_barrier
	s_setprio 1
	s_waitcnt lgkmcnt(0)
	v_mfma_f32_16x16x32_bf16 v[62:65], v[146:149], v[186:189], v[62:65]
	v_mfma_f32_16x16x32_bf16 v[58:61], v[154:157], v[186:189], v[58:61]
	v_mfma_f32_16x16x32_bf16 v[46:49], v[146:149], v[194:197], v[46:49]
	v_mfma_f32_16x16x32_bf16 v[42:45], v[154:157], v[194:197], v[42:45]
	v_mfma_f32_16x16x32_bf16 v[30:33], v[146:149], v[204:207], v[30:33]
	v_mfma_f32_16x16x32_bf16 v[26:29], v[154:157], v[204:207], v[26:29]
	v_mfma_f32_16x16x32_bf16 v[14:17], v[146:149], v[212:215], v[14:17]
	v_mfma_f32_16x16x32_bf16 v[10:13], v[154:157], v[212:215], v[10:13]
	v_mfma_f32_16x16x32_bf16 v[62:65], v[150:153], v[190:193], v[62:65]
	v_mfma_f32_16x16x32_bf16 v[58:61], v[166:169], v[190:193], v[58:61]
	v_mfma_f32_16x16x32_bf16 v[46:49], v[150:153], v[198:201], v[46:49]
	v_mfma_f32_16x16x32_bf16 v[42:45], v[166:169], v[198:201], v[42:45]
	v_mfma_f32_16x16x32_bf16 v[30:33], v[150:153], v[208:211], v[30:33]
	v_mfma_f32_16x16x32_bf16 v[26:29], v[166:169], v[208:211], v[26:29]
	v_mfma_f32_16x16x32_bf16 v[14:17], v[150:153], v[216:219], v[14:17]
	v_mfma_f32_16x16x32_bf16 v[10:13], v[166:169], v[216:219], v[10:13]
	v_mfma_f32_16x16x32_bf16 v[54:57], v[170:173], v[186:189], v[54:57]
	v_mfma_f32_16x16x32_bf16 v[50:53], v[178:181], v[186:189], v[50:53]
	v_mfma_f32_16x16x32_bf16 v[38:41], v[170:173], v[194:197], v[38:41]
	v_mfma_f32_16x16x32_bf16 v[34:37], v[178:181], v[194:197], v[34:37]
	v_mfma_f32_16x16x32_bf16 v[22:25], v[170:173], v[204:207], v[22:25]
	v_mfma_f32_16x16x32_bf16 v[18:21], v[178:181], v[204:207], v[18:21]
	v_mfma_f32_16x16x32_bf16 v[6:9], v[170:173], v[212:215], v[6:9]
	v_mfma_f32_16x16x32_bf16 v[2:5], v[178:181], v[212:215], v[2:5]
	v_mfma_f32_16x16x32_bf16 v[54:57], v[174:177], v[190:193], v[54:57]
	v_mfma_f32_16x16x32_bf16 v[50:53], v[182:185], v[190:193], v[50:53]
	v_mfma_f32_16x16x32_bf16 v[38:41], v[174:177], v[198:201], v[38:41]
	v_mfma_f32_16x16x32_bf16 v[34:37], v[182:185], v[198:201], v[34:37]
	v_mfma_f32_16x16x32_bf16 v[22:25], v[174:177], v[208:211], v[22:25]
	v_mfma_f32_16x16x32_bf16 v[18:21], v[182:185], v[208:211], v[18:21]
	v_mfma_f32_16x16x32_bf16 v[6:9], v[174:177], v[216:219], v[6:9]
	v_mfma_f32_16x16x32_bf16 v[2:5], v[182:185], v[216:219], v[2:5]
	s_setprio 0
	s_barrier
	s_add_i32 s51, 0, 0x18000
	s_add_i32 s52, 0, 0x1c000
	v_add_u32_e32 v166, s51, v159
	v_add_u32_e32 v182, s52, v159
	ds_read_b128 v[146:149], v166
	ds_read_b128 v[150:153], v166 offset:1024
	ds_read_b128 v[154:157], v166 offset:2048
	ds_read_b128 v[166:169], v166 offset:3072
	ds_read_b128 v[170:173], v182
	ds_read_b128 v[174:177], v182 offset:1024
	ds_read_b128 v[178:181], v182 offset:2048
	ds_read_b128 v[182:185], v182 offset:3072
	s_add_u32 s26, s34, 0x160000
	s_addc_u32 s27, s35, 0
	s_mov_b32 m0, s39
	v_lshl_add_u64 v[228:229], s[26:27], 0, v[130:131]
	ds_read_b128 v[186:189], v165 offset:32768
	ds_read_b128 v[190:193], v165 offset:33792
	ds_read_b128 v[194:197], v165 offset:34816
	ds_read_b128 v[198:201], v165 offset:35840
	ds_read_b128 v[204:207], v165 offset:36864
	ds_read_b128 v[208:211], v165 offset:37888
	ds_read_b128 v[212:215], v165 offset:38912
	ds_read_b128 v[216:219], v165 offset:39936
	global_load_lds_dwordx4 v[228:229], off
	v_lshl_add_u64 v[228:229], s[26:27], 0, v[132:133]
	s_mov_b32 m0, s40
	s_nop 0
	global_load_lds_dwordx4 v[228:229], off
	s_waitcnt vmcnt(8)
	s_waitcnt lgkmcnt(0)
	s_barrier
	s_setprio 1
	s_waitcnt lgkmcnt(0)
	v_mfma_f32_16x16x32_bf16 v[126:129], v[146:149], v[186:189], v[126:129]
	v_mfma_f32_16x16x32_bf16 v[122:125], v[154:157], v[186:189], v[122:125]
	v_mfma_f32_16x16x32_bf16 v[110:113], v[146:149], v[194:197], v[110:113]
	v_mfma_f32_16x16x32_bf16 v[106:109], v[154:157], v[194:197], v[106:109]
	v_mfma_f32_16x16x32_bf16 v[94:97], v[146:149], v[204:207], v[94:97]
	v_mfma_f32_16x16x32_bf16 v[90:93], v[154:157], v[204:207], v[90:93]
	v_mfma_f32_16x16x32_bf16 v[78:81], v[146:149], v[212:215], v[78:81]
	v_mfma_f32_16x16x32_bf16 v[74:77], v[154:157], v[212:215], v[74:77]
	v_mfma_f32_16x16x32_bf16 v[126:129], v[150:153], v[190:193], v[126:129]
	v_mfma_f32_16x16x32_bf16 v[122:125], v[166:169], v[190:193], v[122:125]
	v_mfma_f32_16x16x32_bf16 v[110:113], v[150:153], v[198:201], v[110:113]
	v_mfma_f32_16x16x32_bf16 v[106:109], v[166:169], v[198:201], v[106:109]
	v_mfma_f32_16x16x32_bf16 v[94:97], v[150:153], v[208:211], v[94:97]
	v_mfma_f32_16x16x32_bf16 v[90:93], v[166:169], v[208:211], v[90:93]
	v_mfma_f32_16x16x32_bf16 v[78:81], v[150:153], v[216:219], v[78:81]
	v_mfma_f32_16x16x32_bf16 v[74:77], v[166:169], v[216:219], v[74:77]
	v_mfma_f32_16x16x32_bf16 v[118:121], v[170:173], v[186:189], v[118:121]
	v_mfma_f32_16x16x32_bf16 v[114:117], v[178:181], v[186:189], v[114:117]
	v_mfma_f32_16x16x32_bf16 v[102:105], v[170:173], v[194:197], v[102:105]
	v_mfma_f32_16x16x32_bf16 v[98:101], v[178:181], v[194:197], v[98:101]
	v_mfma_f32_16x16x32_bf16 v[86:89], v[170:173], v[204:207], v[86:89]
	v_mfma_f32_16x16x32_bf16 v[82:85], v[178:181], v[204:207], v[82:85]
	v_mfma_f32_16x16x32_bf16 v[70:73], v[170:173], v[212:215], v[70:73]
	v_mfma_f32_16x16x32_bf16 v[66:69], v[178:181], v[212:215], v[66:69]
	v_mfma_f32_16x16x32_bf16 v[118:121], v[174:177], v[190:193], v[118:121]
	v_mfma_f32_16x16x32_bf16 v[114:117], v[182:185], v[190:193], v[114:117]
	v_mfma_f32_16x16x32_bf16 v[102:105], v[174:177], v[198:201], v[102:105]
	v_mfma_f32_16x16x32_bf16 v[98:101], v[182:185], v[198:201], v[98:101]
	v_mfma_f32_16x16x32_bf16 v[86:89], v[174:177], v[208:211], v[86:89]
	v_mfma_f32_16x16x32_bf16 v[82:85], v[182:185], v[208:211], v[82:85]
	v_mfma_f32_16x16x32_bf16 v[70:73], v[174:177], v[216:219], v[70:73]
	v_mfma_f32_16x16x32_bf16 v[66:69], v[182:185], v[216:219], v[66:69]
	s_setprio 0
	s_barrier
	s_add_i32 s26, s51, s19
	v_lshl_add_u64 v[220:221], v[220:221], 0, s[10:11]
	s_mov_b32 m0, s26
	ds_read_b128 v[186:189], v165 offset:49152
	ds_read_b128 v[190:193], v165 offset:50176
	ds_read_b128 v[194:197], v165 offset:51200
	ds_read_b128 v[198:201], v165 offset:52224
	ds_read_b128 v[204:207], v165 offset:53248
	ds_read_b128 v[208:211], v165 offset:54272
	ds_read_b128 v[212:215], v165 offset:55296
	ds_read_b128 v[216:219], v165 offset:56320
	global_load_lds_dwordx4 v[220:221], off
	s_add_i32 m0, s26, 0x2000
	s_add_u32 s26, s30, 0x160080
	v_lshl_add_u64 v[220:221], v[222:223], 0, s[10:11]
	s_addc_u32 s27, s31, 0
	s_add_i32 s30, s52, s19
	global_load_lds_dwordx4 v[220:221], off
	v_lshl_add_u64 v[220:221], s[26:27], 0, v[130:131]
	s_mov_b32 m0, s30
	s_nop 0
	global_load_lds_dwordx4 v[220:221], off
	v_lshl_add_u64 v[220:221], s[26:27], 0, v[132:133]
	s_add_i32 m0, s30, 0x2000
	s_nop 0
	global_load_lds_dwordx4 v[220:221], off
	v_lshl_add_u64 v[220:221], v[224:225], 0, s[10:11]
	s_mov_b32 m0, s41
	s_nop 0
	global_load_lds_dwordx4 v[220:221], off
	v_lshl_add_u64 v[220:221], v[226:227], 0, s[10:11]
	s_mov_b32 m0, s42
	s_nop 0
	global_load_lds_dwordx4 v[220:221], off
	s_waitcnt vmcnt(8)
	s_waitcnt lgkmcnt(0)
	s_barrier
	s_setprio 1
	s_waitcnt lgkmcnt(0)
	v_mfma_f32_16x16x32_bf16 v[62:65], v[146:149], v[186:189], v[62:65]
	v_mfma_f32_16x16x32_bf16 v[58:61], v[154:157], v[186:189], v[58:61]
	v_mfma_f32_16x16x32_bf16 v[46:49], v[146:149], v[194:197], v[46:49]
	v_mfma_f32_16x16x32_bf16 v[42:45], v[154:157], v[194:197], v[42:45]
	v_mfma_f32_16x16x32_bf16 v[30:33], v[146:149], v[204:207], v[30:33]
	v_mfma_f32_16x16x32_bf16 v[26:29], v[154:157], v[204:207], v[26:29]
	v_mfma_f32_16x16x32_bf16 v[14:17], v[146:149], v[212:215], v[14:17]
	v_mfma_f32_16x16x32_bf16 v[10:13], v[154:157], v[212:215], v[10:13]
	v_mfma_f32_16x16x32_bf16 v[62:65], v[150:153], v[190:193], v[62:65]
	v_mfma_f32_16x16x32_bf16 v[58:61], v[166:169], v[190:193], v[58:61]
	v_mfma_f32_16x16x32_bf16 v[46:49], v[150:153], v[198:201], v[46:49]
	v_mfma_f32_16x16x32_bf16 v[42:45], v[166:169], v[198:201], v[42:45]
	v_mfma_f32_16x16x32_bf16 v[30:33], v[150:153], v[208:211], v[30:33]
	v_mfma_f32_16x16x32_bf16 v[26:29], v[166:169], v[208:211], v[26:29]
	v_mfma_f32_16x16x32_bf16 v[14:17], v[150:153], v[216:219], v[14:17]
	v_mfma_f32_16x16x32_bf16 v[10:13], v[166:169], v[216:219], v[10:13]
	v_mfma_f32_16x16x32_bf16 v[54:57], v[170:173], v[186:189], v[54:57]
	v_mfma_f32_16x16x32_bf16 v[50:53], v[178:181], v[186:189], v[50:53]
	v_mfma_f32_16x16x32_bf16 v[38:41], v[170:173], v[194:197], v[38:41]
	v_mfma_f32_16x16x32_bf16 v[34:37], v[178:181], v[194:197], v[34:37]
	v_mfma_f32_16x16x32_bf16 v[22:25], v[170:173], v[204:207], v[22:25]
	v_mfma_f32_16x16x32_bf16 v[18:21], v[178:181], v[204:207], v[18:21]
	v_mfma_f32_16x16x32_bf16 v[6:9], v[170:173], v[212:215], v[6:9]
	v_mfma_f32_16x16x32_bf16 v[2:5], v[178:181], v[212:215], v[2:5]
	v_mfma_f32_16x16x32_bf16 v[54:57], v[174:177], v[190:193], v[54:57]
	v_mfma_f32_16x16x32_bf16 v[50:53], v[182:185], v[190:193], v[50:53]
	v_mfma_f32_16x16x32_bf16 v[38:41], v[174:177], v[198:201], v[38:41]
	v_mfma_f32_16x16x32_bf16 v[34:37], v[182:185], v[198:201], v[34:37]
	v_mfma_f32_16x16x32_bf16 v[22:25], v[174:177], v[208:211], v[22:25]
	v_mfma_f32_16x16x32_bf16 v[18:21], v[182:185], v[208:211], v[18:21]
	v_mfma_f32_16x16x32_bf16 v[6:9], v[174:177], v[216:219], v[6:9]
	v_mfma_f32_16x16x32_bf16 v[2:5], v[182:185], v[216:219], v[2:5]
	s_setprio 0
	s_barrier
	s_add_i32 s50, s50, 2
	s_add_u32 s23, s23, 0x100
	s_addc_u32 s25, s25, 0
	s_cmpk_gt_u32 s50, 0x55
	s_mov_b64 s[26:27], s[28:29]
	s_cbranch_scc0 .LBB0_2149
	s_and_b64 vcc, exec, s[12:13]
	s_cbranch_vccz .LBB0_2152
	s_barrier

.LBB0_2181:
	ds_read_b128 v[146:149], v211
	ds_read_b128 v[150:153], v211 offset:1024
	ds_read_b128 v[154:157], v211 offset:2048
	ds_read_b128 v[158:161], v211 offset:3072
	ds_read_b128 v[162:165], v212
	ds_read_b128 v[166:169], v212 offset:1024
	ds_read_b128 v[170:173], v212 offset:2048
	ds_read_b128 v[174:177], v212 offset:3072
	s_add_u32 s30, s28, 0x100
	s_addc_u32 s31, s29, 0
	s_cmpk_eq_i32 s53, 0x54
	s_cselect_b32 s37, s1, s31
	s_cselect_b32 s36, s0, s30
	s_cselect_b32 s35, s23, s27
	s_cselect_b32 s34, s22, s25
	v_lshl_add_u64 v[222:223], s[28:29], 0, v[138:139]
	s_add_i32 m0, s21, 0xc000
	ds_read_b128 v[178:181], v213
	ds_read_b128 v[182:185], v213 offset:1024
	ds_read_b128 v[186:189], v213 offset:2048
	ds_read_b128 v[190:193], v213 offset:3072
	ds_read_b128 v[194:197], v213 offset:4096
	ds_read_b128 v[198:201], v213 offset:5120
	ds_read_b128 v[214:217], v213 offset:6144
	ds_read_b128 v[218:221], v213 offset:7168
	global_load_lds_dwordx4 v[222:223], off
	v_lshl_add_u64 v[222:223], s[28:29], 0, v[140:141]
	s_add_i32 m0, s21, 0xe000
	s_nop 0
	global_load_lds_dwordx4 v[222:223], off
	s_waitcnt vmcnt(8)
	s_waitcnt lgkmcnt(0)
	s_barrier
	s_setprio 1
	s_waitcnt lgkmcnt(0)
	v_mfma_f32_16x16x32_bf16 v[126:129], v[146:149], v[178:181], v[126:129]
	v_mfma_f32_16x16x32_bf16 v[122:125], v[154:157], v[178:181], v[122:125]
	v_mfma_f32_16x16x32_bf16 v[110:113], v[146:149], v[186:189], v[110:113]
	v_mfma_f32_16x16x32_bf16 v[106:109], v[154:157], v[186:189], v[106:109]
	v_mfma_f32_16x16x32_bf16 v[94:97], v[146:149], v[194:197], v[94:97]
	v_mfma_f32_16x16x32_bf16 v[90:93], v[154:157], v[194:197], v[90:93]
	v_mfma_f32_16x16x32_bf16 v[78:81], v[146:149], v[214:217], v[78:81]
	v_mfma_f32_16x16x32_bf16 v[74:77], v[154:157], v[214:217], v[74:77]
	v_mfma_f32_16x16x32_bf16 v[126:129], v[150:153], v[182:185], v[126:129]
	v_mfma_f32_16x16x32_bf16 v[122:125], v[158:161], v[182:185], v[122:125]
	v_mfma_f32_16x16x32_bf16 v[110:113], v[150:153], v[190:193], v[110:113]
	v_mfma_f32_16x16x32_bf16 v[106:109], v[158:161], v[190:193], v[106:109]
	v_mfma_f32_16x16x32_bf16 v[94:97], v[150:153], v[198:201], v[94:97]
	v_mfma_f32_16x16x32_bf16 v[90:93], v[158:161], v[198:201], v[90:93]
	v_mfma_f32_16x16x32_bf16 v[78:81], v[150:153], v[218:221], v[78:81]
	v_mfma_f32_16x16x32_bf16 v[74:77], v[158:161], v[218:221], v[74:77]
	v_mfma_f32_16x16x32_bf16 v[118:121], v[162:165], v[178:181], v[118:121]
	v_mfma_f32_16x16x32_bf16 v[114:117], v[170:173], v[178:181], v[114:117]
	v_mfma_f32_16x16x32_bf16 v[102:105], v[162:165], v[186:189], v[102:105]
	v_mfma_f32_16x16x32_bf16 v[98:101], v[170:173], v[186:189], v[98:101]
	v_mfma_f32_16x16x32_bf16 v[86:89], v[162:165], v[194:197], v[86:89]
	v_mfma_f32_16x16x32_bf16 v[82:85], v[170:173], v[194:197], v[82:85]
	v_mfma_f32_16x16x32_bf16 v[70:73], v[162:165], v[214:217], v[70:73]
	v_mfma_f32_16x16x32_bf16 v[66:69], v[170:173], v[214:217], v[66:69]
	v_mfma_f32_16x16x32_bf16 v[118:121], v[166:169], v[182:185], v[118:121]
	v_mfma_f32_16x16x32_bf16 v[114:117], v[174:177], v[182:185], v[114:117]
	v_mfma_f32_16x16x32_bf16 v[102:105], v[166:169], v[190:193], v[102:105]
	v_mfma_f32_16x16x32_bf16 v[98:101], v[174:177], v[190:193], v[98:101]
	v_mfma_f32_16x16x32_bf16 v[86:89], v[166:169], v[198:201], v[86:89]
	v_mfma_f32_16x16x32_bf16 v[82:85], v[174:177], v[198:201], v[82:85]
	v_mfma_f32_16x16x32_bf16 v[70:73], v[166:169], v[218:221], v[70:73]
	v_mfma_f32_16x16x32_bf16 v[66:69], v[174:177], v[218:221], v[66:69]
	s_setprio 0
	s_barrier
	s_add_i32 s28, s47, s19
	v_lshl_add_u64 v[222:223], s[34:35], 0, v[130:131]
	s_mov_b32 m0, s28
	ds_read_b128 v[178:181], v213 offset:16384
	ds_read_b128 v[182:185], v213 offset:17408
	ds_read_b128 v[186:189], v213 offset:18432
	ds_read_b128 v[190:193], v213 offset:19456
	ds_read_b128 v[194:197], v213 offset:20480
	ds_read_b128 v[198:201], v213 offset:21504
	ds_read_b128 v[214:217], v213 offset:22528
	ds_read_b128 v[218:221], v213 offset:23552
	global_load_lds_dwordx4 v[222:223], off
	s_add_i32 m0, s28, 0x2000
	s_add_u32 s28, s34, 0x160000
	v_lshl_add_u64 v[224:225], s[34:35], 0, v[132:133]
	s_addc_u32 s29, s35, 0
	s_add_i32 s54, s48, s19
	global_load_lds_dwordx4 v[224:225], off
	v_lshl_add_u64 v[226:227], s[28:29], 0, v[130:131]
	s_mov_b32 m0, s54
	v_lshl_add_u64 v[228:229], s[36:37], 0, v[132:133]
	global_load_lds_dwordx4 v[226:227], off
	v_lshl_add_u64 v[226:227], s[28:29], 0, v[132:133]
	s_add_i32 m0, s54, 0x2000
	s_nop 0
	global_load_lds_dwordx4 v[226:227], off
	v_lshl_add_u64 v[226:227], s[36:37], 0, v[130:131]
	s_mov_b32 m0, s21
	s_nop 0
	global_load_lds_dwordx4 v[226:227], off
	s_mov_b32 m0, s38
	s_nop 0
	global_load_lds_dwordx4 v[228:229], off
	s_waitcnt vmcnt(8)
	s_waitcnt lgkmcnt(0)
	s_barrier
	s_setprio 1
	s_waitcnt lgkmcnt(0)
	v_mfma_f32_16x16x32_bf16 v[62:65], v[146:149], v[178:181], v[62:65]
	v_mfma_f32_16x16x32_bf16 v[58:61], v[154:157], v[178:181], v[58:61]
	v_mfma_f32_16x16x32_bf16 v[46:49], v[146:149], v[186:189], v[46:49]
	v_mfma_f32_16x16x32_bf16 v[42:45], v[154:157], v[186:189], v[42:45]
	v_mfma_f32_16x16x32_bf16 v[30:33], v[146:149], v[194:197], v[30:33]
	v_mfma_f32_16x16x32_bf16 v[26:29], v[154:157], v[194:197], v[26:29]
	v_mfma_f32_16x16x32_bf16 v[14:17], v[146:149], v[214:217], v[14:17]
	v_mfma_f32_16x16x32_bf16 v[10:13], v[154:157], v[214:217], v[10:13]
	v_mfma_f32_16x16x32_bf16 v[62:65], v[150:153], v[182:185], v[62:65]
	v_mfma_f32_16x16x32_bf16 v[58:61], v[158:161], v[182:185], v[58:61]
	v_mfma_f32_16x16x32_bf16 v[46:49], v[150:153], v[190:193], v[46:49]
	v_mfma_f32_16x16x32_bf16 v[42:45], v[158:161], v[190:193], v[42:45]
	v_mfma_f32_16x16x32_bf16 v[30:33], v[150:153], v[198:201], v[30:33]
	v_mfma_f32_16x16x32_bf16 v[26:29], v[158:161], v[198:201], v[26:29]
	v_mfma_f32_16x16x32_bf16 v[14:17], v[150:153], v[218:221], v[14:17]
	v_mfma_f32_16x16x32_bf16 v[10:13], v[158:161], v[218:221], v[10:13]
	v_mfma_f32_16x16x32_bf16 v[54:57], v[162:165], v[178:181], v[54:57]
	v_mfma_f32_16x16x32_bf16 v[50:53], v[170:173], v[178:181], v[50:53]
	v_mfma_f32_16x16x32_bf16 v[38:41], v[162:165], v[186:189], v[38:41]
	v_mfma_f32_16x16x32_bf16 v[34:37], v[170:173], v[186:189], v[34:37]
	v_mfma_f32_16x16x32_bf16 v[22:25], v[162:165], v[194:197], v[22:25]
	v_mfma_f32_16x16x32_bf16 v[18:21], v[170:173], v[194:197], v[18:21]
	v_mfma_f32_16x16x32_bf16 v[6:9], v[162:165], v[214:217], v[6:9]
	v_mfma_f32_16x16x32_bf16 v[2:5], v[170:173], v[214:217], v[2:5]
	v_mfma_f32_16x16x32_bf16 v[54:57], v[166:169], v[182:185], v[54:57]
	v_mfma_f32_16x16x32_bf16 v[50:53], v[174:177], v[182:185], v[50:53]
	v_mfma_f32_16x16x32_bf16 v[38:41], v[166:169], v[190:193], v[38:41]
	v_mfma_f32_16x16x32_bf16 v[34:37], v[174:177], v[190:193], v[34:37]
	v_mfma_f32_16x16x32_bf16 v[22:25], v[166:169], v[198:201], v[22:25]
	v_mfma_f32_16x16x32_bf16 v[18:21], v[174:177], v[198:201], v[18:21]
	v_mfma_f32_16x16x32_bf16 v[6:9], v[166:169], v[218:221], v[6:9]
	v_mfma_f32_16x16x32_bf16 v[2:5], v[174:177], v[218:221], v[2:5]
	s_setprio 0
	s_barrier
	s_add_i32 s54, 0, 0x18000
	s_add_i32 s55, 0, 0x1c000
	v_add_u32_e32 v158, s54, v205
	v_add_u32_e32 v174, s55, v205
	ds_read_b128 v[146:149], v158
	ds_read_b128 v[150:153], v158 offset:1024
	ds_read_b128 v[154:157], v158 offset:2048
	ds_read_b128 v[158:161], v158 offset:3072
	ds_read_b128 v[162:165], v174
	ds_read_b128 v[166:169], v174 offset:1024
	ds_read_b128 v[170:173], v174 offset:2048
	ds_read_b128 v[174:177], v174 offset:3072
	s_add_u32 s28, s36, 0x160000
	s_addc_u32 s29, s37, 0
	s_mov_b32 m0, s39
	v_lshl_add_u64 v[230:231], s[28:29], 0, v[130:131]
	ds_read_b128 v[178:181], v213 offset:32768
	ds_read_b128 v[182:185], v213 offset:33792
	ds_read_b128 v[186:189], v213 offset:34816
	ds_read_b128 v[190:193], v213 offset:35840
	ds_read_b128 v[194:197], v213 offset:36864
	ds_read_b128 v[198:201], v213 offset:37888
	ds_read_b128 v[214:217], v213 offset:38912
	ds_read_b128 v[218:221], v213 offset:39936
	global_load_lds_dwordx4 v[230:231], off
	v_lshl_add_u64 v[230:231], s[28:29], 0, v[132:133]
	s_mov_b32 m0, s40
	s_nop 0
	global_load_lds_dwordx4 v[230:231], off
	s_waitcnt vmcnt(8)
	s_waitcnt lgkmcnt(0)
	s_barrier
	s_setprio 1
	s_waitcnt lgkmcnt(0)
	v_mfma_f32_16x16x32_bf16 v[126:129], v[146:149], v[178:181], v[126:129]
	v_mfma_f32_16x16x32_bf16 v[122:125], v[154:157], v[178:181], v[122:125]
	v_mfma_f32_16x16x32_bf16 v[110:113], v[146:149], v[186:189], v[110:113]
	v_mfma_f32_16x16x32_bf16 v[106:109], v[154:157], v[186:189], v[106:109]
	v_mfma_f32_16x16x32_bf16 v[94:97], v[146:149], v[194:197], v[94:97]
	v_mfma_f32_16x16x32_bf16 v[90:93], v[154:157], v[194:197], v[90:93]
	v_mfma_f32_16x16x32_bf16 v[78:81], v[146:149], v[214:217], v[78:81]
	v_mfma_f32_16x16x32_bf16 v[74:77], v[154:157], v[214:217], v[74:77]
	v_mfma_f32_16x16x32_bf16 v[126:129], v[150:153], v[182:185], v[126:129]
	v_mfma_f32_16x16x32_bf16 v[122:125], v[158:161], v[182:185], v[122:125]
	v_mfma_f32_16x16x32_bf16 v[110:113], v[150:153], v[190:193], v[110:113]
	v_mfma_f32_16x16x32_bf16 v[106:109], v[158:161], v[190:193], v[106:109]
	v_mfma_f32_16x16x32_bf16 v[94:97], v[150:153], v[198:201], v[94:97]
	v_mfma_f32_16x16x32_bf16 v[90:93], v[158:161], v[198:201], v[90:93]
	v_mfma_f32_16x16x32_bf16 v[78:81], v[150:153], v[218:221], v[78:81]
	v_mfma_f32_16x16x32_bf16 v[74:77], v[158:161], v[218:221], v[74:77]
	v_mfma_f32_16x16x32_bf16 v[118:121], v[162:165], v[178:181], v[118:121]
	v_mfma_f32_16x16x32_bf16 v[114:117], v[170:173], v[178:181], v[114:117]
	v_mfma_f32_16x16x32_bf16 v[102:105], v[162:165], v[186:189], v[102:105]
	v_mfma_f32_16x16x32_bf16 v[98:101], v[170:173], v[186:189], v[98:101]
	v_mfma_f32_16x16x32_bf16 v[86:89], v[162:165], v[194:197], v[86:89]
	v_mfma_f32_16x16x32_bf16 v[82:85], v[170:173], v[194:197], v[82:85]
	v_mfma_f32_16x16x32_bf16 v[70:73], v[162:165], v[214:217], v[70:73]
	v_mfma_f32_16x16x32_bf16 v[66:69], v[170:173], v[214:217], v[66:69]
	v_mfma_f32_16x16x32_bf16 v[118:121], v[166:169], v[182:185], v[118:121]
	v_mfma_f32_16x16x32_bf16 v[114:117], v[174:177], v[182:185], v[114:117]
	v_mfma_f32_16x16x32_bf16 v[102:105], v[166:169], v[190:193], v[102:105]
	v_mfma_f32_16x16x32_bf16 v[98:101], v[174:177], v[190:193], v[98:101]
	v_mfma_f32_16x16x32_bf16 v[86:89], v[166:169], v[198:201], v[86:89]
	v_mfma_f32_16x16x32_bf16 v[82:85], v[174:177], v[198:201], v[82:85]
	v_mfma_f32_16x16x32_bf16 v[70:73], v[166:169], v[218:221], v[70:73]
	v_mfma_f32_16x16x32_bf16 v[66:69], v[174:177], v[218:221], v[66:69]
	s_setprio 0
	s_barrier
	s_add_i32 s28, s54, s19
	v_lshl_add_u64 v[222:223], v[222:223], 0, s[12:13]
	s_mov_b32 m0, s28
	ds_read_b128 v[178:181], v213 offset:49152
	ds_read_b128 v[182:185], v213 offset:50176
	ds_read_b128 v[186:189], v213 offset:51200
	ds_read_b128 v[190:193], v213 offset:52224
	ds_read_b128 v[194:197], v213 offset:53248
	ds_read_b128 v[198:201], v213 offset:54272
	ds_read_b128 v[214:217], v213 offset:55296
	ds_read_b128 v[218:221], v213 offset:56320
	global_load_lds_dwordx4 v[222:223], off
	s_add_i32 m0, s28, 0x2000
	s_add_u32 s28, s34, 0x160080
	v_lshl_add_u64 v[222:223], v[224:225], 0, s[12:13]
	s_addc_u32 s29, s35, 0
	s_add_i32 s34, s55, s19
	global_load_lds_dwordx4 v[222:223], off
	v_lshl_add_u64 v[222:223], s[28:29], 0, v[130:131]
	s_mov_b32 m0, s34
	s_nop 0
	global_load_lds_dwordx4 v[222:223], off
	v_lshl_add_u64 v[222:223], s[28:29], 0, v[132:133]
	s_add_i32 m0, s34, 0x2000
	s_nop 0
	global_load_lds_dwordx4 v[222:223], off
	v_lshl_add_u64 v[222:223], v[226:227], 0, s[12:13]
	s_mov_b32 m0, s41
	s_nop 0
	global_load_lds_dwordx4 v[222:223], off
	v_lshl_add_u64 v[222:223], v[228:229], 0, s[12:13]
	s_mov_b32 m0, s42
	s_nop 0
	global_load_lds_dwordx4 v[222:223], off
	s_waitcnt vmcnt(8)
	s_waitcnt lgkmcnt(0)
	s_barrier
	s_setprio 1
	s_waitcnt lgkmcnt(0)
	v_mfma_f32_16x16x32_bf16 v[62:65], v[146:149], v[178:181], v[62:65]
	v_mfma_f32_16x16x32_bf16 v[58:61], v[154:157], v[178:181], v[58:61]
	v_mfma_f32_16x16x32_bf16 v[46:49], v[146:149], v[186:189], v[46:49]
	v_mfma_f32_16x16x32_bf16 v[42:45], v[154:157], v[186:189], v[42:45]
	v_mfma_f32_16x16x32_bf16 v[30:33], v[146:149], v[194:197], v[30:33]
	v_mfma_f32_16x16x32_bf16 v[26:29], v[154:157], v[194:197], v[26:29]
	v_mfma_f32_16x16x32_bf16 v[14:17], v[146:149], v[214:217], v[14:17]
	v_mfma_f32_16x16x32_bf16 v[10:13], v[154:157], v[214:217], v[10:13]
	v_mfma_f32_16x16x32_bf16 v[62:65], v[150:153], v[182:185], v[62:65]
	v_mfma_f32_16x16x32_bf16 v[58:61], v[158:161], v[182:185], v[58:61]
	v_mfma_f32_16x16x32_bf16 v[46:49], v[150:153], v[190:193], v[46:49]
	v_mfma_f32_16x16x32_bf16 v[42:45], v[158:161], v[190:193], v[42:45]
	v_mfma_f32_16x16x32_bf16 v[30:33], v[150:153], v[198:201], v[30:33]
	v_mfma_f32_16x16x32_bf16 v[26:29], v[158:161], v[198:201], v[26:29]
	v_mfma_f32_16x16x32_bf16 v[14:17], v[150:153], v[218:221], v[14:17]
	v_mfma_f32_16x16x32_bf16 v[10:13], v[158:161], v[218:221], v[10:13]
	v_mfma_f32_16x16x32_bf16 v[54:57], v[162:165], v[178:181], v[54:57]
	v_mfma_f32_16x16x32_bf16 v[50:53], v[170:173], v[178:181], v[50:53]
	v_mfma_f32_16x16x32_bf16 v[38:41], v[162:165], v[186:189], v[38:41]
	v_mfma_f32_16x16x32_bf16 v[34:37], v[170:173], v[186:189], v[34:37]
	v_mfma_f32_16x16x32_bf16 v[22:25], v[162:165], v[194:197], v[22:25]
	v_mfma_f32_16x16x32_bf16 v[18:21], v[170:173], v[194:197], v[18:21]
	v_mfma_f32_16x16x32_bf16 v[6:9], v[162:165], v[214:217], v[6:9]
	v_mfma_f32_16x16x32_bf16 v[2:5], v[170:173], v[214:217], v[2:5]
	v_mfma_f32_16x16x32_bf16 v[54:57], v[166:169], v[182:185], v[54:57]
	v_mfma_f32_16x16x32_bf16 v[50:53], v[174:177], v[182:185], v[50:53]
	v_mfma_f32_16x16x32_bf16 v[38:41], v[166:169], v[190:193], v[38:41]
	v_mfma_f32_16x16x32_bf16 v[34:37], v[174:177], v[190:193], v[34:37]
	v_mfma_f32_16x16x32_bf16 v[22:25], v[166:169], v[198:201], v[22:25]
	v_mfma_f32_16x16x32_bf16 v[18:21], v[174:177], v[198:201], v[18:21]
	v_mfma_f32_16x16x32_bf16 v[6:9], v[166:169], v[218:221], v[6:9]
	v_mfma_f32_16x16x32_bf16 v[2:5], v[174:177], v[218:221], v[2:5]
	s_setprio 0
	s_barrier
	s_add_i32 s53, s53, 2
	s_add_u32 s25, s25, 0x100
	s_addc_u32 s27, s27, 0
	s_cmpk_gt_u32 s53, 0x55
	s_mov_b64 s[28:29], s[30:31]
	s_cbranch_scc0 .LBB0_2181
	s_and_b64 vcc, exec, s[14:15]
	s_cbranch_vccz .LBB0_2184
	s_barrier
